# quarter ring loop: the two B-half LDS-DMA pieces of a K-tile issued among the MFMAs, the two A pieces in the load section
# baseline (speedup 1.0000x reference)
; #define PG8_STAGE(bufoff, gbase, voff) do { _Pragma("unroll") for (int _i = 0; _i < 2; ++_i) \
;         __builtin_amdgcn_global_load_lds((const unsigned*)((const char*)(gbase) + (voff)[_i]), (PG8_LAS unsigned*)(lds + (bufoff) + ldsw + _i * 8192), 16, 0, 0); } while (0)
; #define PG8_LDA(dst, b, h) do { _Pragma("unroll") for (int m = 0; m < 4; ++m) _Pragma("unroll") for (int k = 0; k < 2; ++k) dst[m][k] = *(const PG8_LAS bf16x8*)(lds + PG8_SA(b, h) + aoff + m * 2048 + k * 1024); } while (0)
; #define PG8_LDB(dst, b, h) do { _Pragma("unroll") for (int n = 0; n < 2; ++n) _Pragma("unroll") for (int k = 0; k < 2; ++k) dst[n][k] = *(const PG8_LAS bf16x8*)(lds + PG8_SB(b, h) + boff + n * 2048 + k * 1024); } while (0)
; #define PG8_MMA(ai, bj, At, Bt) do { __builtin_amdgcn_s_setprio(1); _Pragma("unroll") for (int m = 0; m < 4; ++m) _Pragma("unroll") for (int n = 0; n < 2; ++n) _Pragma("unroll") for (int k = 0; k < 2; ++k) \
;         acc[ai][bj][m][n] = __builtin_amdgcn_mfma_f32_16x16x32_bf16(Bt[n][k], At[m][k], acc[ai][bj][m][n], 0, 0, 0); __builtin_amdgcn_s_setprio(0); } while (0)
; #define PG8_WAIT_V(n) asm volatile("s_waitcnt vmcnt(" #n ")" ::: "memory")
; template <class Epi, class Sched, bool ALIGN_EPI = false, bool SP2 = false>
; __device__ __forceinline__ void gemm_phase(PG8_LAS unsigned char* lds, const Gemm g, const Sched& S, const Epi& E) {
;     ...
;             PG8_LDB(B0, 0, 0); PG8_LDB(B1, 0, 1); PG8_SCHED; PG8_LDA(At, 0, 0); PG8_STAGE(PG8_SA(1, 1), a1 + hstep, voffA);
;             PG8_WAIT_V(8); PG8_WAIT_L(0); PG8_BAR; PG8_MMA(0, 0, At, B0); PG8_MMA(0, 1, At, B1); PG8_BAR; PG8_SCHED;
;             PG8_LDA(At, 0, 1); PG8_STAGE(PG8_SB(0, 0), b2, voffB); PG8_STAGE(PG8_SB(0, 1), b2 + hstep, voffB); PG8_STAGE(PG8_SA(0, 0), a2, voffA);
;             PG8_WAIT_V(8); PG8_WAIT_L(0); PG8_BAR; PG8_MMA(1, 0, At, B0); PG8_MMA(1, 1, At, B1); PG8_BAR; PG8_SCHED;
;             PG8_LDB(B0, 1, 0); PG8_LDB(B1, 1, 1); PG8_SCHED; PG8_LDA(At, 1, 0); PG8_STAGE(PG8_SA(0, 1), a2 + hstep, voffA);
;             PG8_WAIT_V(8); PG8_WAIT_L(0); PG8_BAR; PG8_MMA(0, 0, At, B0); PG8_MMA(0, 1, At, B1); PG8_BAR; PG8_SCHED;
;             PG8_LDA(At, 1, 1); PG8_STAGE(PG8_SB(1, 0), b3, voffB); PG8_STAGE(PG8_SB(1, 1), b3 + hstep, voffB); PG8_STAGE(PG8_SA(1, 0), a3, voffA);
;             PG8_WAIT_V(8); PG8_WAIT_L(0); PG8_BAR; PG8_MMA(1, 0, At, B0); PG8_MMA(1, 1, At, B1); PG8_BAR; PG8_SCHED;
.Lkq_1:
	s_waitcnt vmcnt(0)
	s_barrier
	s_mov_b64 s[76:77], s[48:49]
	s_add_u32 vcc_lo, s80, 0xffffff80
	s_addc_u32 vcc_hi, s81, -1
	s_add_u32 s76, s76, 0x80
	s_addc_u32 s77, s77, 0
	s_add_u32 vcc_lo, vcc_lo, 0x80
	s_addc_u32 vcc_hi, vcc_hi, 0
	v_lshl_add_u64 v[136:137], s[76:77], 0, v[0:1]
	s_add_i32 m0, s94, 0x4000
	v_lshl_add_u64 v[144:145], s[76:77], 0, v[130:131]
	global_load_lds_dwordx4 v[136:137], off
	s_add_i32 m0, s94, 0x6000
	s_nop 0
	global_load_lds_dwordx4 v[144:145], off
	v_lshl_add_u64 v[182:183], vcc, 0, v[0:1]
	s_add_i32 m0, s93, 0x14000
	v_lshl_add_u64 v[236:237], vcc, 0, v[130:131]
	global_load_lds_dwordx4 v[182:183], off
	s_add_i32 m0, s93, 0x16000
	s_nop 0
	global_load_lds_dwordx4 v[236:237], off
	s_add_u32 s76, s76, 0x80
	s_addc_u32 s77, s77, 0
	s_add_u32 vcc_lo, vcc_lo, 0x80
	s_addc_u32 vcc_hi, vcc_hi, 0
	s_mov_b32 s82, 3
	s_add_i32 s59, s79, -1
	v_add_u32_e32 v136, 0x10000, v147
	ds_read_b128 v[148:151], v136
	ds_read_b128 v[152:155], v136 offset:1024
	ds_read_b128 v[156:159], v136 offset:2048
	ds_read_b128 v[160:163], v136 offset:3072
	ds_read_b128 v[202:205], v165
	ds_read_b128 v[208:211], v165 offset:1024
	ds_read_b128 v[212:215], v165 offset:2048
	ds_read_b128 v[216:219], v165 offset:3072
	ds_read_b128 v[220:223], v165 offset:4096
	ds_read_b128 v[224:227], v165 offset:5120
	ds_read_b128 v[228:231], v165 offset:6144
	ds_read_b128 v[232:235], v165 offset:7168
	v_lshl_add_u64 v[136:137], s[76:77], 0, v[0:1]
	s_add_i32 m0, s94, 0xc000
	v_lshl_add_u64 v[144:145], s[76:77], 0, v[130:131]
	global_load_lds_dwordx4 v[136:137], off
	s_add_i32 m0, s94, 0xe000
	s_nop 0
	global_load_lds_dwordx4 v[144:145], off
	s_waitcnt vmcnt(6)
	s_waitcnt lgkmcnt(0)
	s_barrier
	s_setprio 1
	v_mfma_f32_16x16x32_bf16 v[126:129], v[148:151], v[202:205], 0
	v_mfma_f32_16x16x32_bf16 v[122:125], v[156:159], v[202:205], 0
	v_mfma_f32_16x16x32_bf16 v[110:113], v[148:151], v[212:215], 0
	v_lshl_add_u64 v[182:183], vcc, 0, v[0:1]
	s_add_i32 m0, s93, 0x1c000
	v_lshl_add_u64 v[236:237], vcc, 0, v[130:131]
	global_load_lds_dwordx4 v[182:183], off
	v_mfma_f32_16x16x32_bf16 v[106:109], v[156:159], v[212:215], 0
	v_mfma_f32_16x16x32_bf16 v[94:97], v[148:151], v[220:223], 0
	v_mfma_f32_16x16x32_bf16 v[90:93], v[156:159], v[220:223], 0
	v_mfma_f32_16x16x32_bf16 v[78:81], v[148:151], v[228:231], 0
	v_mfma_f32_16x16x32_bf16 v[74:77], v[156:159], v[228:231], 0
	v_mfma_f32_16x16x32_bf16 v[126:129], v[152:155], v[208:211], v[126:129]
	s_add_i32 m0, s93, 0x1e000
	s_nop 0
	global_load_lds_dwordx4 v[236:237], off
	v_mfma_f32_16x16x32_bf16 v[122:125], v[160:163], v[208:211], v[122:125]
	v_mfma_f32_16x16x32_bf16 v[110:113], v[152:155], v[216:219], v[110:113]
	v_mfma_f32_16x16x32_bf16 v[106:109], v[160:163], v[216:219], v[106:109]
	v_mfma_f32_16x16x32_bf16 v[94:97], v[152:155], v[224:227], v[94:97]
	v_mfma_f32_16x16x32_bf16 v[90:93], v[160:163], v[224:227], v[90:93]
	v_mfma_f32_16x16x32_bf16 v[78:81], v[152:155], v[232:235], v[78:81]
	v_mfma_f32_16x16x32_bf16 v[74:77], v[160:163], v[232:235], v[74:77]
	s_cmp_lt_u32 s82, s59
	s_cselect_b32 s83, 0x80, 0
	s_add_u32 s76, s76, s83
	s_addc_u32 s77, s77, 0
	s_add_u32 vcc_lo, vcc_lo, s83
	s_addc_u32 vcc_hi, vcc_hi, 0
	s_add_i32 s82, s82, 1
	s_setprio 0
	s_barrier
	v_add_u32_e32 v136, 0x18000, v147
	ds_read_b128 v[148:151], v136
	ds_read_b128 v[152:155], v136 offset:1024
	ds_read_b128 v[156:159], v136 offset:2048
	ds_read_b128 v[160:163], v136 offset:3072
	ds_read_b128 v[202:205], v165 offset:32768
	ds_read_b128 v[208:211], v165 offset:33792
	ds_read_b128 v[212:215], v165 offset:34816
	ds_read_b128 v[216:219], v165 offset:35840
	ds_read_b128 v[220:223], v165 offset:36864
	ds_read_b128 v[224:227], v165 offset:37888
	ds_read_b128 v[228:231], v165 offset:38912
	ds_read_b128 v[232:235], v165 offset:39936
	v_lshl_add_u64 v[136:137], s[76:77], 0, v[0:1]
	s_add_i32 m0, s94, 0x0
	v_lshl_add_u64 v[144:145], s[76:77], 0, v[130:131]
	global_load_lds_dwordx4 v[136:137], off
	s_add_i32 m0, s94, 0x2000
	s_nop 0
	global_load_lds_dwordx4 v[144:145], off
	s_waitcnt vmcnt(6)
	s_waitcnt lgkmcnt(0)
	s_barrier
	s_setprio 1
	v_mfma_f32_16x16x32_bf16 v[126:129], v[148:151], v[202:205], v[126:129]
	v_mfma_f32_16x16x32_bf16 v[122:125], v[156:159], v[202:205], v[122:125]
	v_mfma_f32_16x16x32_bf16 v[110:113], v[148:151], v[212:215], v[110:113]
	v_lshl_add_u64 v[182:183], vcc, 0, v[0:1]
	s_add_i32 m0, s93, 0x10000
	v_lshl_add_u64 v[236:237], vcc, 0, v[130:131]
	global_load_lds_dwordx4 v[182:183], off
	v_mfma_f32_16x16x32_bf16 v[106:109], v[156:159], v[212:215], v[106:109]
	v_mfma_f32_16x16x32_bf16 v[94:97], v[148:151], v[220:223], v[94:97]
	v_mfma_f32_16x16x32_bf16 v[90:93], v[156:159], v[220:223], v[90:93]
	v_mfma_f32_16x16x32_bf16 v[78:81], v[148:151], v[228:231], v[78:81]
	v_mfma_f32_16x16x32_bf16 v[74:77], v[156:159], v[228:231], v[74:77]
	v_mfma_f32_16x16x32_bf16 v[126:129], v[152:155], v[208:211], v[126:129]
	s_add_i32 m0, s93, 0x12000
	s_nop 0
	global_load_lds_dwordx4 v[236:237], off
	v_mfma_f32_16x16x32_bf16 v[122:125], v[160:163], v[208:211], v[122:125]
	v_mfma_f32_16x16x32_bf16 v[110:113], v[152:155], v[216:219], v[110:113]
	v_mfma_f32_16x16x32_bf16 v[106:109], v[160:163], v[216:219], v[106:109]
	v_mfma_f32_16x16x32_bf16 v[94:97], v[152:155], v[224:227], v[94:97]
	v_mfma_f32_16x16x32_bf16 v[90:93], v[160:163], v[224:227], v[90:93]
	v_mfma_f32_16x16x32_bf16 v[78:81], v[152:155], v[232:235], v[78:81]
	v_mfma_f32_16x16x32_bf16 v[74:77], v[160:163], v[232:235], v[74:77]
	s_cmp_lt_u32 s82, s59
	s_cselect_b32 s83, 0x80, 0
	s_add_u32 s76, s76, s83
	s_addc_u32 s77, s77, 0
	s_add_u32 vcc_lo, vcc_lo, s83
	s_addc_u32 vcc_hi, vcc_hi, 0
	s_add_i32 s82, s82, 1
	s_setprio 0
	s_barrier
; #define PG8_STAGE(bufoff, gbase, voff) do { _Pragma("unroll") for (int _i = 0; _i < 2; ++_i) \
;         __builtin_amdgcn_global_load_lds((const unsigned*)((const char*)(gbase) + (voff)[_i]), (PG8_LAS unsigned*)(lds + (bufoff) + ldsw + _i * 8192), 16, 0, 0); } while (0)
; #define PG8_LDA(dst, b, h) do { _Pragma("unroll") for (int m = 0; m < 4; ++m) _Pragma("unroll") for (int k = 0; k < 2; ++k) dst[m][k] = *(const PG8_LAS bf16x8*)(lds + PG8_SA(b, h) + aoff + m * 2048 + k * 1024); } while (0)
; #define PG8_LDB(dst, b, h) do { _Pragma("unroll") for (int n = 0; n < 2; ++n) _Pragma("unroll") for (int k = 0; k < 2; ++k) dst[n][k] = *(const PG8_LAS bf16x8*)(lds + PG8_SB(b, h) + boff + n * 2048 + k * 1024); } while (0)
; #define PG8_MMA(ai, bj, At, Bt) do { __builtin_amdgcn_s_setprio(1); _Pragma("unroll") for (int m = 0; m < 4; ++m) _Pragma("unroll") for (int n = 0; n < 2; ++n) _Pragma("unroll") for (int k = 0; k < 2; ++k) \
;         acc[ai][bj][m][n] = __builtin_amdgcn_mfma_f32_16x16x32_bf16(Bt[n][k], At[m][k], acc[ai][bj][m][n], 0, 0, 0); __builtin_amdgcn_s_setprio(0); } while (0)
; #define PG8_WAIT_V(n) asm volatile("s_waitcnt vmcnt(" #n ")" ::: "memory")
; template <class Epi, class Sched, bool ALIGN_EPI = false, bool SP2 = false>
; __device__ __forceinline__ void gemm_phase(PG8_LAS unsigned char* lds, const Gemm g, const Sched& S, const Epi& E) {
;     ...
;             PG8_LDB(B0, 0, 0); PG8_LDB(B1, 0, 1); PG8_SCHED; PG8_LDA(At, 0, 0); PG8_STAGE(PG8_SA(1, 1), a1 + hstep, voffA);
;             PG8_WAIT_V(8); PG8_WAIT_L(0); PG8_BAR; PG8_MMA(0, 0, At, B0); PG8_MMA(0, 1, At, B1); PG8_BAR; PG8_SCHED;
;             PG8_LDA(At, 0, 1); PG8_STAGE(PG8_SB(0, 0), b2, voffB); PG8_STAGE(PG8_SB(0, 1), b2 + hstep, voffB); PG8_STAGE(PG8_SA(0, 0), a2, voffA);
;             PG8_WAIT_V(8); PG8_WAIT_L(0); PG8_BAR; PG8_MMA(1, 0, At, B0); PG8_MMA(1, 1, At, B1); PG8_BAR; PG8_SCHED;
;             PG8_LDB(B0, 1, 0); PG8_LDB(B1, 1, 1); PG8_SCHED; PG8_LDA(At, 1, 0); PG8_STAGE(PG8_SA(0, 1), a2 + hstep, voffA);
;             PG8_WAIT_V(8); PG8_WAIT_L(0); PG8_BAR; PG8_MMA(0, 0, At, B0); PG8_MMA(0, 1, At, B1); PG8_BAR; PG8_SCHED;
;             PG8_LDA(At, 1, 1); PG8_STAGE(PG8_SB(1, 0), b3, voffB); PG8_STAGE(PG8_SB(1, 1), b3 + hstep, voffB); PG8_STAGE(PG8_SA(1, 0), a3, voffA);
;             PG8_WAIT_V(8); PG8_WAIT_L(0); PG8_BAR; PG8_MMA(1, 0, At, B0); PG8_MMA(1, 1, At, B1); PG8_BAR; PG8_SCHED;
	v_add_u32_e32 v136, 0x14000, v147
	ds_read_b128 v[148:151], v136
	ds_read_b128 v[152:155], v136 offset:1024
	ds_read_b128 v[156:159], v136 offset:2048
	ds_read_b128 v[160:163], v136 offset:3072
	ds_read_b128 v[202:205], v165 offset:16384
	ds_read_b128 v[208:211], v165 offset:17408
	ds_read_b128 v[212:215], v165 offset:18432
	ds_read_b128 v[216:219], v165 offset:19456
	ds_read_b128 v[220:223], v165 offset:20480
	ds_read_b128 v[224:227], v165 offset:21504
	ds_read_b128 v[228:231], v165 offset:22528
	ds_read_b128 v[232:235], v165 offset:23552
	v_lshl_add_u64 v[136:137], s[76:77], 0, v[0:1]
	s_add_i32 m0, s94, 0x8000
	v_lshl_add_u64 v[144:145], s[76:77], 0, v[130:131]
	global_load_lds_dwordx4 v[136:137], off
	s_add_i32 m0, s94, 0xa000
	s_nop 0
	global_load_lds_dwordx4 v[144:145], off
	s_waitcnt vmcnt(6)
	s_waitcnt lgkmcnt(0)
	s_barrier
	s_setprio 1
	v_mfma_f32_16x16x32_bf16 v[126:129], v[148:151], v[202:205], v[126:129]
	v_mfma_f32_16x16x32_bf16 v[122:125], v[156:159], v[202:205], v[122:125]
	v_mfma_f32_16x16x32_bf16 v[110:113], v[148:151], v[212:215], v[110:113]
	v_lshl_add_u64 v[182:183], vcc, 0, v[0:1]
	s_add_i32 m0, s93, 0x18000
	v_lshl_add_u64 v[236:237], vcc, 0, v[130:131]
	global_load_lds_dwordx4 v[182:183], off
	v_mfma_f32_16x16x32_bf16 v[106:109], v[156:159], v[212:215], v[106:109]
	v_mfma_f32_16x16x32_bf16 v[94:97], v[148:151], v[220:223], v[94:97]
	v_mfma_f32_16x16x32_bf16 v[90:93], v[156:159], v[220:223], v[90:93]
	v_mfma_f32_16x16x32_bf16 v[78:81], v[148:151], v[228:231], v[78:81]
	v_mfma_f32_16x16x32_bf16 v[74:77], v[156:159], v[228:231], v[74:77]
	v_mfma_f32_16x16x32_bf16 v[126:129], v[152:155], v[208:211], v[126:129]
	s_add_i32 m0, s93, 0x1a000
	s_nop 0
	global_load_lds_dwordx4 v[236:237], off
	v_mfma_f32_16x16x32_bf16 v[122:125], v[160:163], v[208:211], v[122:125]
	v_mfma_f32_16x16x32_bf16 v[110:113], v[152:155], v[216:219], v[110:113]
	v_mfma_f32_16x16x32_bf16 v[106:109], v[160:163], v[216:219], v[106:109]
	v_mfma_f32_16x16x32_bf16 v[94:97], v[152:155], v[224:227], v[94:97]
	v_mfma_f32_16x16x32_bf16 v[90:93], v[160:163], v[224:227], v[90:93]
	v_mfma_f32_16x16x32_bf16 v[78:81], v[152:155], v[232:235], v[78:81]
	v_mfma_f32_16x16x32_bf16 v[74:77], v[160:163], v[232:235], v[74:77]
	s_cmp_lt_u32 s82, s59
	s_cselect_b32 s83, 0x80, 0
	s_add_u32 s76, s76, s83
	s_addc_u32 s77, s77, 0
	s_add_u32 vcc_lo, vcc_lo, s83
	s_addc_u32 vcc_hi, vcc_hi, 0
	s_add_i32 s82, s82, 1
	s_setprio 0
	s_barrier
	v_add_u32_e32 v136, 0x1c000, v147
	ds_read_b128 v[148:151], v136
	ds_read_b128 v[152:155], v136 offset:1024
	ds_read_b128 v[156:159], v136 offset:2048
	ds_read_b128 v[160:163], v136 offset:3072
	ds_read_b128 v[202:205], v165 offset:49152
	ds_read_b128 v[208:211], v165 offset:50176
	ds_read_b128 v[212:215], v165 offset:51200
	ds_read_b128 v[216:219], v165 offset:52224
	ds_read_b128 v[220:223], v165 offset:53248
	ds_read_b128 v[224:227], v165 offset:54272
	ds_read_b128 v[228:231], v165 offset:55296
	ds_read_b128 v[232:235], v165 offset:56320
	v_lshl_add_u64 v[136:137], s[76:77], 0, v[0:1]
	s_add_i32 m0, s94, 0x4000
	v_lshl_add_u64 v[144:145], s[76:77], 0, v[130:131]
	global_load_lds_dwordx4 v[136:137], off
	s_add_i32 m0, s94, 0x6000
	s_nop 0
	global_load_lds_dwordx4 v[144:145], off
	s_waitcnt vmcnt(6)
	s_waitcnt lgkmcnt(0)
	s_barrier
	s_setprio 1
	v_mfma_f32_16x16x32_bf16 v[126:129], v[148:151], v[202:205], v[126:129]
	v_mfma_f32_16x16x32_bf16 v[122:125], v[156:159], v[202:205], v[122:125]
	v_mfma_f32_16x16x32_bf16 v[110:113], v[148:151], v[212:215], v[110:113]
	v_lshl_add_u64 v[182:183], vcc, 0, v[0:1]
	s_add_i32 m0, s93, 0x14000
	v_lshl_add_u64 v[236:237], vcc, 0, v[130:131]
	global_load_lds_dwordx4 v[182:183], off
	v_mfma_f32_16x16x32_bf16 v[106:109], v[156:159], v[212:215], v[106:109]
	v_mfma_f32_16x16x32_bf16 v[94:97], v[148:151], v[220:223], v[94:97]
	v_mfma_f32_16x16x32_bf16 v[90:93], v[156:159], v[220:223], v[90:93]
	v_mfma_f32_16x16x32_bf16 v[78:81], v[148:151], v[228:231], v[78:81]
	v_mfma_f32_16x16x32_bf16 v[74:77], v[156:159], v[228:231], v[74:77]
	v_mfma_f32_16x16x32_bf16 v[126:129], v[152:155], v[208:211], v[126:129]
	s_add_i32 m0, s93, 0x16000
	s_nop 0
	global_load_lds_dwordx4 v[236:237], off
	v_mfma_f32_16x16x32_bf16 v[122:125], v[160:163], v[208:211], v[122:125]
	v_mfma_f32_16x16x32_bf16 v[110:113], v[152:155], v[216:219], v[110:113]
	v_mfma_f32_16x16x32_bf16 v[106:109], v[160:163], v[216:219], v[106:109]
	v_mfma_f32_16x16x32_bf16 v[94:97], v[152:155], v[224:227], v[94:97]
	v_mfma_f32_16x16x32_bf16 v[90:93], v[160:163], v[224:227], v[90:93]
	v_mfma_f32_16x16x32_bf16 v[78:81], v[152:155], v[232:235], v[78:81]
	v_mfma_f32_16x16x32_bf16 v[74:77], v[160:163], v[232:235], v[74:77]
	s_cmp_lt_u32 s82, s59
	s_cselect_b32 s83, 0x80, 0
	s_add_u32 s76, s76, s83
	s_addc_u32 s77, s77, 0
	s_add_u32 vcc_lo, vcc_lo, s83
	s_addc_u32 vcc_hi, vcc_hi, 0
	s_add_i32 s82, s82, 1
	s_setprio 0
	s_barrier
	s_add_i32 s83, s82, -3
	s_cmp_lt_u32 s83, s79
	s_cbranch_scc0 .Lkq_1_post
; #define PG8_STAGE(bufoff, gbase, voff) do { _Pragma("unroll") for (int _i = 0; _i < 2; ++_i) \
;         __builtin_amdgcn_global_load_lds((const unsigned*)((const char*)(gbase) + (voff)[_i]), (PG8_LAS unsigned*)(lds + (bufoff) + ldsw + _i * 8192), 16, 0, 0); } while (0)
; #define PG8_LDA(dst, b, h) do { _Pragma("unroll") for (int m = 0; m < 4; ++m) _Pragma("unroll") for (int k = 0; k < 2; ++k) dst[m][k] = *(const PG8_LAS bf16x8*)(lds + PG8_SA(b, h) + aoff + m * 2048 + k * 1024); } while (0)
; #define PG8_LDB(dst, b, h) do { _Pragma("unroll") for (int n = 0; n < 2; ++n) _Pragma("unroll") for (int k = 0; k < 2; ++k) dst[n][k] = *(const PG8_LAS bf16x8*)(lds + PG8_SB(b, h) + boff + n * 2048 + k * 1024); } while (0)
; #define PG8_MMA(ai, bj, At, Bt) do { __builtin_amdgcn_s_setprio(1); _Pragma("unroll") for (int m = 0; m < 4; ++m) _Pragma("unroll") for (int n = 0; n < 2; ++n) _Pragma("unroll") for (int k = 0; k < 2; ++k) \
;         acc[ai][bj][m][n] = __builtin_amdgcn_mfma_f32_16x16x32_bf16(Bt[n][k], At[m][k], acc[ai][bj][m][n], 0, 0, 0); __builtin_amdgcn_s_setprio(0); } while (0)
; #define PG8_WAIT_V(n) asm volatile("s_waitcnt vmcnt(" #n ")" ::: "memory")
; template <class Epi, class Sched, bool ALIGN_EPI = false, bool SP2 = false>
; __device__ __forceinline__ void gemm_phase(PG8_LAS unsigned char* lds, const Gemm g, const Sched& S, const Epi& E) {
;     ...
;             PG8_LDB(B0, 0, 0); PG8_LDB(B1, 0, 1); PG8_SCHED; PG8_LDA(At, 0, 0); PG8_STAGE(PG8_SA(1, 1), a1 + hstep, voffA);
;             PG8_WAIT_V(8); PG8_WAIT_L(0); PG8_BAR; PG8_MMA(0, 0, At, B0); PG8_MMA(0, 1, At, B1); PG8_BAR; PG8_SCHED;
;             PG8_LDA(At, 0, 1); PG8_STAGE(PG8_SB(0, 0), b2, voffB); PG8_STAGE(PG8_SB(0, 1), b2 + hstep, voffB); PG8_STAGE(PG8_SA(0, 0), a2, voffA);
;             PG8_WAIT_V(8); PG8_WAIT_L(0); PG8_BAR; PG8_MMA(1, 0, At, B0); PG8_MMA(1, 1, At, B1); PG8_BAR; PG8_SCHED;
;             PG8_LDB(B0, 1, 0); PG8_LDB(B1, 1, 1); PG8_SCHED; PG8_LDA(At, 1, 0); PG8_STAGE(PG8_SA(0, 1), a2 + hstep, voffA);
;             PG8_WAIT_V(8); PG8_WAIT_L(0); PG8_BAR; PG8_MMA(0, 0, At, B0); PG8_MMA(0, 1, At, B1); PG8_BAR; PG8_SCHED;
;             PG8_LDA(At, 1, 1); PG8_STAGE(PG8_SB(1, 0), b3, voffB); PG8_STAGE(PG8_SB(1, 1), b3 + hstep, voffB); PG8_STAGE(PG8_SA(1, 0), a3, voffA);
;             PG8_WAIT_V(8); PG8_WAIT_L(0); PG8_BAR; PG8_MMA(1, 0, At, B0); PG8_MMA(1, 1, At, B1); PG8_BAR; PG8_SCHED;
.Lkq_1_loop:
	v_add_u32_e32 v136, 0x10000, v147
	ds_read_b128 v[148:151], v136
	ds_read_b128 v[152:155], v136 offset:1024
	ds_read_b128 v[156:159], v136 offset:2048
	ds_read_b128 v[160:163], v136 offset:3072
	ds_read_b128 v[202:205], v165
	ds_read_b128 v[208:211], v165 offset:1024
	ds_read_b128 v[212:215], v165 offset:2048
	ds_read_b128 v[216:219], v165 offset:3072
	ds_read_b128 v[220:223], v165 offset:4096
	ds_read_b128 v[224:227], v165 offset:5120
	ds_read_b128 v[228:231], v165 offset:6144
	ds_read_b128 v[232:235], v165 offset:7168
	v_lshl_add_u64 v[136:137], s[76:77], 0, v[0:1]
	s_add_i32 m0, s94, 0xc000
	v_lshl_add_u64 v[144:145], s[76:77], 0, v[130:131]
	global_load_lds_dwordx4 v[136:137], off
	s_add_i32 m0, s94, 0xe000
	s_nop 0
	global_load_lds_dwordx4 v[144:145], off
	s_waitcnt vmcnt(6)
	s_waitcnt lgkmcnt(0)
	s_barrier
	s_setprio 1
	v_mfma_f32_16x16x32_bf16 v[126:129], v[148:151], v[202:205], v[126:129]
	v_mfma_f32_16x16x32_bf16 v[122:125], v[156:159], v[202:205], v[122:125]
	v_mfma_f32_16x16x32_bf16 v[110:113], v[148:151], v[212:215], v[110:113]
	v_lshl_add_u64 v[182:183], vcc, 0, v[0:1]
	s_add_i32 m0, s93, 0x1c000
	v_lshl_add_u64 v[236:237], vcc, 0, v[130:131]
	global_load_lds_dwordx4 v[182:183], off
	v_mfma_f32_16x16x32_bf16 v[106:109], v[156:159], v[212:215], v[106:109]
	v_mfma_f32_16x16x32_bf16 v[94:97], v[148:151], v[220:223], v[94:97]
	v_mfma_f32_16x16x32_bf16 v[90:93], v[156:159], v[220:223], v[90:93]
	v_mfma_f32_16x16x32_bf16 v[78:81], v[148:151], v[228:231], v[78:81]
	v_mfma_f32_16x16x32_bf16 v[74:77], v[156:159], v[228:231], v[74:77]
	v_mfma_f32_16x16x32_bf16 v[126:129], v[152:155], v[208:211], v[126:129]
	s_add_i32 m0, s93, 0x1e000
	s_nop 0
	global_load_lds_dwordx4 v[236:237], off
	v_mfma_f32_16x16x32_bf16 v[122:125], v[160:163], v[208:211], v[122:125]
	v_mfma_f32_16x16x32_bf16 v[110:113], v[152:155], v[216:219], v[110:113]
	v_mfma_f32_16x16x32_bf16 v[106:109], v[160:163], v[216:219], v[106:109]
	v_mfma_f32_16x16x32_bf16 v[94:97], v[152:155], v[224:227], v[94:97]
	v_mfma_f32_16x16x32_bf16 v[90:93], v[160:163], v[224:227], v[90:93]
	v_mfma_f32_16x16x32_bf16 v[78:81], v[152:155], v[232:235], v[78:81]
	v_mfma_f32_16x16x32_bf16 v[74:77], v[160:163], v[232:235], v[74:77]
	s_cmp_lt_u32 s82, s59
	s_cselect_b32 s83, 0x80, 0
	s_add_u32 s76, s76, s83
	s_addc_u32 s77, s77, 0
	s_add_u32 vcc_lo, vcc_lo, s83
	s_addc_u32 vcc_hi, vcc_hi, 0
	s_add_i32 s82, s82, 1
	s_setprio 0
	s_barrier
	v_add_u32_e32 v136, 0x18000, v147
	ds_read_b128 v[148:151], v136
	ds_read_b128 v[152:155], v136 offset:1024
	ds_read_b128 v[156:159], v136 offset:2048
	ds_read_b128 v[160:163], v136 offset:3072
	ds_read_b128 v[202:205], v165 offset:32768
	ds_read_b128 v[208:211], v165 offset:33792
	ds_read_b128 v[212:215], v165 offset:34816
	ds_read_b128 v[216:219], v165 offset:35840
	ds_read_b128 v[220:223], v165 offset:36864
	ds_read_b128 v[224:227], v165 offset:37888
	ds_read_b128 v[228:231], v165 offset:38912
	ds_read_b128 v[232:235], v165 offset:39936
	v_lshl_add_u64 v[136:137], s[76:77], 0, v[0:1]
	s_add_i32 m0, s94, 0x0
	v_lshl_add_u64 v[144:145], s[76:77], 0, v[130:131]
	global_load_lds_dwordx4 v[136:137], off
	s_add_i32 m0, s94, 0x2000
	s_nop 0
	global_load_lds_dwordx4 v[144:145], off
	s_waitcnt vmcnt(6)
	s_waitcnt lgkmcnt(0)
	s_barrier
	s_setprio 1
	v_mfma_f32_16x16x32_bf16 v[126:129], v[148:151], v[202:205], v[126:129]
	v_mfma_f32_16x16x32_bf16 v[122:125], v[156:159], v[202:205], v[122:125]
	v_mfma_f32_16x16x32_bf16 v[110:113], v[148:151], v[212:215], v[110:113]
	v_lshl_add_u64 v[182:183], vcc, 0, v[0:1]
	s_add_i32 m0, s93, 0x10000
	v_lshl_add_u64 v[236:237], vcc, 0, v[130:131]
	global_load_lds_dwordx4 v[182:183], off
	v_mfma_f32_16x16x32_bf16 v[106:109], v[156:159], v[212:215], v[106:109]
	v_mfma_f32_16x16x32_bf16 v[94:97], v[148:151], v[220:223], v[94:97]
	v_mfma_f32_16x16x32_bf16 v[90:93], v[156:159], v[220:223], v[90:93]
	v_mfma_f32_16x16x32_bf16 v[78:81], v[148:151], v[228:231], v[78:81]
	v_mfma_f32_16x16x32_bf16 v[74:77], v[156:159], v[228:231], v[74:77]
	v_mfma_f32_16x16x32_bf16 v[126:129], v[152:155], v[208:211], v[126:129]
	s_add_i32 m0, s93, 0x12000
	s_nop 0
	global_load_lds_dwordx4 v[236:237], off
	v_mfma_f32_16x16x32_bf16 v[122:125], v[160:163], v[208:211], v[122:125]
	v_mfma_f32_16x16x32_bf16 v[110:113], v[152:155], v[216:219], v[110:113]
	v_mfma_f32_16x16x32_bf16 v[106:109], v[160:163], v[216:219], v[106:109]
	v_mfma_f32_16x16x32_bf16 v[94:97], v[152:155], v[224:227], v[94:97]
	v_mfma_f32_16x16x32_bf16 v[90:93], v[160:163], v[224:227], v[90:93]
	v_mfma_f32_16x16x32_bf16 v[78:81], v[152:155], v[232:235], v[78:81]
	v_mfma_f32_16x16x32_bf16 v[74:77], v[160:163], v[232:235], v[74:77]
	s_cmp_lt_u32 s82, s59
	s_cselect_b32 s83, 0x80, 0
	s_add_u32 s76, s76, s83
	s_addc_u32 s77, s77, 0
	s_add_u32 vcc_lo, vcc_lo, s83
	s_addc_u32 vcc_hi, vcc_hi, 0
	s_add_i32 s82, s82, 1
	s_setprio 0
	s_barrier
; #define PG8_STAGE(bufoff, gbase, voff) do { _Pragma("unroll") for (int _i = 0; _i < 2; ++_i) \
;         __builtin_amdgcn_global_load_lds((const unsigned*)((const char*)(gbase) + (voff)[_i]), (PG8_LAS unsigned*)(lds + (bufoff) + ldsw + _i * 8192), 16, 0, 0); } while (0)
; #define PG8_LDA(dst, b, h) do { _Pragma("unroll") for (int m = 0; m < 4; ++m) _Pragma("unroll") for (int k = 0; k < 2; ++k) dst[m][k] = *(const PG8_LAS bf16x8*)(lds + PG8_SA(b, h) + aoff + m * 2048 + k * 1024); } while (0)
; #define PG8_LDB(dst, b, h) do { _Pragma("unroll") for (int n = 0; n < 2; ++n) _Pragma("unroll") for (int k = 0; k < 2; ++k) dst[n][k] = *(const PG8_LAS bf16x8*)(lds + PG8_SB(b, h) + boff + n * 2048 + k * 1024); } while (0)
; #define PG8_MMA(ai, bj, At, Bt) do { __builtin_amdgcn_s_setprio(1); _Pragma("unroll") for (int m = 0; m < 4; ++m) _Pragma("unroll") for (int n = 0; n < 2; ++n) _Pragma("unroll") for (int k = 0; k < 2; ++k) \
;         acc[ai][bj][m][n] = __builtin_amdgcn_mfma_f32_16x16x32_bf16(Bt[n][k], At[m][k], acc[ai][bj][m][n], 0, 0, 0); __builtin_amdgcn_s_setprio(0); } while (0)
; #define PG8_WAIT_V(n) asm volatile("s_waitcnt vmcnt(" #n ")" ::: "memory")
; template <class Epi, class Sched, bool ALIGN_EPI = false, bool SP2 = false>
; __device__ __forceinline__ void gemm_phase(PG8_LAS unsigned char* lds, const Gemm g, const Sched& S, const Epi& E) {
;     ...
;             PG8_LDB(B0, 0, 0); PG8_LDB(B1, 0, 1); PG8_SCHED; PG8_LDA(At, 0, 0); PG8_STAGE(PG8_SA(1, 1), a1 + hstep, voffA);
;             PG8_WAIT_V(8); PG8_WAIT_L(0); PG8_BAR; PG8_MMA(0, 0, At, B0); PG8_MMA(0, 1, At, B1); PG8_BAR; PG8_SCHED;
;             PG8_LDA(At, 0, 1); PG8_STAGE(PG8_SB(0, 0), b2, voffB); PG8_STAGE(PG8_SB(0, 1), b2 + hstep, voffB); PG8_STAGE(PG8_SA(0, 0), a2, voffA);
;             PG8_WAIT_V(8); PG8_WAIT_L(0); PG8_BAR; PG8_MMA(1, 0, At, B0); PG8_MMA(1, 1, At, B1); PG8_BAR; PG8_SCHED;
;             PG8_LDB(B0, 1, 0); PG8_LDB(B1, 1, 1); PG8_SCHED; PG8_LDA(At, 1, 0); PG8_STAGE(PG8_SA(0, 1), a2 + hstep, voffA);
;             PG8_WAIT_V(8); PG8_WAIT_L(0); PG8_BAR; PG8_MMA(0, 0, At, B0); PG8_MMA(0, 1, At, B1); PG8_BAR; PG8_SCHED;
;             PG8_LDA(At, 1, 1); PG8_STAGE(PG8_SB(1, 0), b3, voffB); PG8_STAGE(PG8_SB(1, 1), b3 + hstep, voffB); PG8_STAGE(PG8_SA(1, 0), a3, voffA);
;             PG8_WAIT_V(8); PG8_WAIT_L(0); PG8_BAR; PG8_MMA(1, 0, At, B0); PG8_MMA(1, 1, At, B1); PG8_BAR; PG8_SCHED;
	v_add_u32_e32 v136, 0x14000, v147
	ds_read_b128 v[148:151], v136
	ds_read_b128 v[152:155], v136 offset:1024
	ds_read_b128 v[156:159], v136 offset:2048
	ds_read_b128 v[160:163], v136 offset:3072
	ds_read_b128 v[202:205], v165 offset:16384
	ds_read_b128 v[208:211], v165 offset:17408
	ds_read_b128 v[212:215], v165 offset:18432
	ds_read_b128 v[216:219], v165 offset:19456
	ds_read_b128 v[220:223], v165 offset:20480
	ds_read_b128 v[224:227], v165 offset:21504
	ds_read_b128 v[228:231], v165 offset:22528
	ds_read_b128 v[232:235], v165 offset:23552
	v_lshl_add_u64 v[136:137], s[76:77], 0, v[0:1]
	s_add_i32 m0, s94, 0x8000
	v_lshl_add_u64 v[144:145], s[76:77], 0, v[130:131]
	global_load_lds_dwordx4 v[136:137], off
	s_add_i32 m0, s94, 0xa000
	s_nop 0
	global_load_lds_dwordx4 v[144:145], off
	s_waitcnt vmcnt(6)
	s_waitcnt lgkmcnt(0)
	s_barrier
	s_setprio 1
	v_mfma_f32_16x16x32_bf16 v[126:129], v[148:151], v[202:205], v[126:129]
	v_mfma_f32_16x16x32_bf16 v[122:125], v[156:159], v[202:205], v[122:125]
	v_mfma_f32_16x16x32_bf16 v[110:113], v[148:151], v[212:215], v[110:113]
	v_lshl_add_u64 v[182:183], vcc, 0, v[0:1]
	s_add_i32 m0, s93, 0x18000
	v_lshl_add_u64 v[236:237], vcc, 0, v[130:131]
	global_load_lds_dwordx4 v[182:183], off
	v_mfma_f32_16x16x32_bf16 v[106:109], v[156:159], v[212:215], v[106:109]
	v_mfma_f32_16x16x32_bf16 v[94:97], v[148:151], v[220:223], v[94:97]
	v_mfma_f32_16x16x32_bf16 v[90:93], v[156:159], v[220:223], v[90:93]
	v_mfma_f32_16x16x32_bf16 v[78:81], v[148:151], v[228:231], v[78:81]
	v_mfma_f32_16x16x32_bf16 v[74:77], v[156:159], v[228:231], v[74:77]
	v_mfma_f32_16x16x32_bf16 v[126:129], v[152:155], v[208:211], v[126:129]
	s_add_i32 m0, s93, 0x1a000
	s_nop 0
	global_load_lds_dwordx4 v[236:237], off
	v_mfma_f32_16x16x32_bf16 v[122:125], v[160:163], v[208:211], v[122:125]
	v_mfma_f32_16x16x32_bf16 v[110:113], v[152:155], v[216:219], v[110:113]
	v_mfma_f32_16x16x32_bf16 v[106:109], v[160:163], v[216:219], v[106:109]
	v_mfma_f32_16x16x32_bf16 v[94:97], v[152:155], v[224:227], v[94:97]
	v_mfma_f32_16x16x32_bf16 v[90:93], v[160:163], v[224:227], v[90:93]
	v_mfma_f32_16x16x32_bf16 v[78:81], v[152:155], v[232:235], v[78:81]
	v_mfma_f32_16x16x32_bf16 v[74:77], v[160:163], v[232:235], v[74:77]
	s_cmp_lt_u32 s82, s59
	s_cselect_b32 s83, 0x80, 0
	s_add_u32 s76, s76, s83
	s_addc_u32 s77, s77, 0
	s_add_u32 vcc_lo, vcc_lo, s83
	s_addc_u32 vcc_hi, vcc_hi, 0
	s_add_i32 s82, s82, 1
	s_setprio 0
	s_barrier
	v_add_u32_e32 v136, 0x1c000, v147
	ds_read_b128 v[148:151], v136
	ds_read_b128 v[152:155], v136 offset:1024
	ds_read_b128 v[156:159], v136 offset:2048
	ds_read_b128 v[160:163], v136 offset:3072
	ds_read_b128 v[202:205], v165 offset:49152
	ds_read_b128 v[208:211], v165 offset:50176
	ds_read_b128 v[212:215], v165 offset:51200
	ds_read_b128 v[216:219], v165 offset:52224
	ds_read_b128 v[220:223], v165 offset:53248
	ds_read_b128 v[224:227], v165 offset:54272
	ds_read_b128 v[228:231], v165 offset:55296
	ds_read_b128 v[232:235], v165 offset:56320
	v_lshl_add_u64 v[136:137], s[76:77], 0, v[0:1]
	s_add_i32 m0, s94, 0x4000
	v_lshl_add_u64 v[144:145], s[76:77], 0, v[130:131]
	global_load_lds_dwordx4 v[136:137], off
	s_add_i32 m0, s94, 0x6000
	s_nop 0
	global_load_lds_dwordx4 v[144:145], off
	s_waitcnt vmcnt(6)
	s_waitcnt lgkmcnt(0)
	s_barrier
	s_setprio 1
	v_mfma_f32_16x16x32_bf16 v[126:129], v[148:151], v[202:205], v[126:129]
	v_mfma_f32_16x16x32_bf16 v[122:125], v[156:159], v[202:205], v[122:125]
	v_mfma_f32_16x16x32_bf16 v[110:113], v[148:151], v[212:215], v[110:113]
	v_lshl_add_u64 v[182:183], vcc, 0, v[0:1]
	s_add_i32 m0, s93, 0x14000
	v_lshl_add_u64 v[236:237], vcc, 0, v[130:131]
	global_load_lds_dwordx4 v[182:183], off
	v_mfma_f32_16x16x32_bf16 v[106:109], v[156:159], v[212:215], v[106:109]
	v_mfma_f32_16x16x32_bf16 v[94:97], v[148:151], v[220:223], v[94:97]
	v_mfma_f32_16x16x32_bf16 v[90:93], v[156:159], v[220:223], v[90:93]
	v_mfma_f32_16x16x32_bf16 v[78:81], v[148:151], v[228:231], v[78:81]
	v_mfma_f32_16x16x32_bf16 v[74:77], v[156:159], v[228:231], v[74:77]
	v_mfma_f32_16x16x32_bf16 v[126:129], v[152:155], v[208:211], v[126:129]
	s_add_i32 m0, s93, 0x16000
	s_nop 0
	global_load_lds_dwordx4 v[236:237], off
	v_mfma_f32_16x16x32_bf16 v[122:125], v[160:163], v[208:211], v[122:125]
	v_mfma_f32_16x16x32_bf16 v[110:113], v[152:155], v[216:219], v[110:113]
	v_mfma_f32_16x16x32_bf16 v[106:109], v[160:163], v[216:219], v[106:109]
	v_mfma_f32_16x16x32_bf16 v[94:97], v[152:155], v[224:227], v[94:97]
	v_mfma_f32_16x16x32_bf16 v[90:93], v[160:163], v[224:227], v[90:93]
	v_mfma_f32_16x16x32_bf16 v[78:81], v[152:155], v[232:235], v[78:81]
	v_mfma_f32_16x16x32_bf16 v[74:77], v[160:163], v[232:235], v[74:77]
	s_cmp_lt_u32 s82, s59
	s_cselect_b32 s83, 0x80, 0
	s_add_u32 s76, s76, s83
	s_addc_u32 s77, s77, 0
	s_add_u32 vcc_lo, vcc_lo, s83
	s_addc_u32 vcc_hi, vcc_hi, 0
	s_add_i32 s82, s82, 1
	s_setprio 0
	s_barrier
	s_add_i32 s83, s82, -3
	s_cmp_lt_u32 s83, s79
	s_cbranch_scc1 .Lkq_1_loop

; #define PG8_STAGE(bufoff, gbase, voff) do { _Pragma("unroll") for (int _i = 0; _i < 2; ++_i) \
;         __builtin_amdgcn_global_load_lds((const unsigned*)((const char*)(gbase) + (voff)[_i]), (PG8_LAS unsigned*)(lds + (bufoff) + ldsw + _i * 8192), 16, 0, 0); } while (0)
; #define PG8_LDA(dst, b, h) do { _Pragma("unroll") for (int m = 0; m < 4; ++m) _Pragma("unroll") for (int k = 0; k < 2; ++k) dst[m][k] = *(const PG8_LAS bf16x8*)(lds + PG8_SA(b, h) + aoff + m * 2048 + k * 1024); } while (0)
; #define PG8_LDB(dst, b, h) do { _Pragma("unroll") for (int n = 0; n < 2; ++n) _Pragma("unroll") for (int k = 0; k < 2; ++k) dst[n][k] = *(const PG8_LAS bf16x8*)(lds + PG8_SB(b, h) + boff + n * 2048 + k * 1024); } while (0)
; #define PG8_MMA(ai, bj, At, Bt) do { __builtin_amdgcn_s_setprio(1); _Pragma("unroll") for (int m = 0; m < 4; ++m) _Pragma("unroll") for (int n = 0; n < 2; ++n) _Pragma("unroll") for (int k = 0; k < 2; ++k) \
;         acc[ai][bj][m][n] = __builtin_amdgcn_mfma_f32_16x16x32_bf16(Bt[n][k], At[m][k], acc[ai][bj][m][n], 0, 0, 0); __builtin_amdgcn_s_setprio(0); } while (0)
; #define PG8_WAIT_V(n) asm volatile("s_waitcnt vmcnt(" #n ")" ::: "memory")
; template <class Epi, class Sched, bool ALIGN_EPI = false, bool SP2 = false>
; __device__ __forceinline__ void gemm_phase(PG8_LAS unsigned char* lds, const Gemm g, const Sched& S, const Epi& E) {
;     ...
;             PG8_LDB(B0, 0, 0); PG8_LDB(B1, 0, 1); PG8_SCHED; PG8_LDA(At, 0, 0); PG8_STAGE(PG8_SA(1, 1), a1 + hstep, voffA);
;             PG8_WAIT_V(8); PG8_WAIT_L(0); PG8_BAR; PG8_MMA(0, 0, At, B0); PG8_MMA(0, 1, At, B1); PG8_BAR; PG8_SCHED;
;             PG8_LDA(At, 0, 1); PG8_STAGE(PG8_SB(0, 0), b2, voffB); PG8_STAGE(PG8_SB(0, 1), b2 + hstep, voffB); PG8_STAGE(PG8_SA(0, 0), a2, voffA);
;             PG8_WAIT_V(8); PG8_WAIT_L(0); PG8_BAR; PG8_MMA(1, 0, At, B0); PG8_MMA(1, 1, At, B1); PG8_BAR; PG8_SCHED;
;             PG8_LDB(B0, 1, 0); PG8_LDB(B1, 1, 1); PG8_SCHED; PG8_LDA(At, 1, 0); PG8_STAGE(PG8_SA(0, 1), a2 + hstep, voffA);
;             PG8_WAIT_V(8); PG8_WAIT_L(0); PG8_BAR; PG8_MMA(0, 0, At, B0); PG8_MMA(0, 1, At, B1); PG8_BAR; PG8_SCHED;
;             PG8_LDA(At, 1, 1); PG8_STAGE(PG8_SB(1, 0), b3, voffB); PG8_STAGE(PG8_SB(1, 1), b3 + hstep, voffB); PG8_STAGE(PG8_SA(1, 0), a3, voffA);
;             PG8_WAIT_V(8); PG8_WAIT_L(0); PG8_BAR; PG8_MMA(1, 0, At, B0); PG8_MMA(1, 1, At, B1); PG8_BAR; PG8_SCHED;
.Lkq_2:
	s_waitcnt vmcnt(0)
	s_barrier
	s_mov_b64 s[76:77], s[48:49]
	s_add_u32 vcc_lo, s80, 0xffffff80
	s_addc_u32 vcc_hi, s81, -1
	s_add_u32 s76, s76, s10
	s_addc_u32 s77, s77, 0
	v_lshl_add_u64 v[136:137], s[76:77], 0, v[0:1]
	s_add_i32 m0, s94, 0xc000
	v_lshl_add_u64 v[144:145], s[76:77], 0, v[130:131]
	global_load_lds_dwordx4 v[136:137], off
	s_add_i32 m0, s94, 0xe000
	s_nop 0
	global_load_lds_dwordx4 v[144:145], off
	s_add_u32 s76, s76, 0x80
	s_addc_u32 s77, s77, 0
	s_add_u32 vcc_lo, vcc_lo, 0x80
	s_addc_u32 vcc_hi, vcc_hi, 0
	v_lshl_add_u64 v[136:137], s[76:77], 0, v[0:1]
	s_add_i32 m0, s94, 0x0
	v_lshl_add_u64 v[144:145], s[76:77], 0, v[130:131]
	global_load_lds_dwordx4 v[136:137], off
	s_add_i32 m0, s94, 0x2000
	s_nop 0
	global_load_lds_dwordx4 v[144:145], off
	v_lshl_add_u64 v[182:183], vcc, 0, v[0:1]
	s_add_i32 m0, s93, 0x14000
	v_lshl_add_u64 v[236:237], vcc, 0, v[130:131]
	global_load_lds_dwordx4 v[182:183], off
	s_add_i32 m0, s93, 0x16000
	s_nop 0
	global_load_lds_dwordx4 v[236:237], off
	s_add_u32 s76, s76, 0x80
	s_addc_u32 s77, s77, 0
	s_add_u32 vcc_lo, vcc_lo, 0x80
	s_addc_u32 vcc_hi, vcc_hi, 0
	s_mov_b32 s82, 3
	s_add_i32 s59, s79, -1
	v_add_u32_e32 v136, 0x10000, v147
	ds_read_b128 v[148:151], v136
	ds_read_b128 v[152:155], v136 offset:1024
	ds_read_b128 v[156:159], v136 offset:2048
	ds_read_b128 v[160:163], v136 offset:3072
	ds_read_b128 v[202:205], v165 offset:16384
	ds_read_b128 v[208:211], v165 offset:17408
	ds_read_b128 v[212:215], v165 offset:18432
	ds_read_b128 v[216:219], v165 offset:19456
	ds_read_b128 v[220:223], v165 offset:20480
	ds_read_b128 v[224:227], v165 offset:21504
	ds_read_b128 v[228:231], v165 offset:22528
	ds_read_b128 v[232:235], v165 offset:23552
	v_lshl_add_u64 v[136:137], s[76:77], 0, v[0:1]
	s_add_i32 m0, s94, 0x8000
	v_lshl_add_u64 v[144:145], s[76:77], 0, v[130:131]
	global_load_lds_dwordx4 v[136:137], off
	s_add_i32 m0, s94, 0xa000
	s_nop 0
	global_load_lds_dwordx4 v[144:145], off
	s_waitcnt vmcnt(6)
	s_waitcnt lgkmcnt(0)
	s_barrier
	s_setprio 1
	v_mfma_f32_16x16x32_bf16 v[62:65], v[148:151], v[202:205], 0
	v_mfma_f32_16x16x32_bf16 v[58:61], v[156:159], v[202:205], 0
	v_mfma_f32_16x16x32_bf16 v[46:49], v[148:151], v[212:215], 0
	v_lshl_add_u64 v[182:183], vcc, 0, v[0:1]
	s_add_i32 m0, s93, 0x1c000
	v_lshl_add_u64 v[236:237], vcc, 0, v[130:131]
	global_load_lds_dwordx4 v[182:183], off
	v_mfma_f32_16x16x32_bf16 v[42:45], v[156:159], v[212:215], 0
	v_mfma_f32_16x16x32_bf16 v[30:33], v[148:151], v[220:223], 0
	v_mfma_f32_16x16x32_bf16 v[26:29], v[156:159], v[220:223], 0
	v_mfma_f32_16x16x32_bf16 v[14:17], v[148:151], v[228:231], 0
	v_mfma_f32_16x16x32_bf16 v[10:13], v[156:159], v[228:231], 0
	v_mfma_f32_16x16x32_bf16 v[62:65], v[152:155], v[208:211], v[62:65]
	s_add_i32 m0, s93, 0x1e000
	s_nop 0
	global_load_lds_dwordx4 v[236:237], off
	v_mfma_f32_16x16x32_bf16 v[58:61], v[160:163], v[208:211], v[58:61]
	v_mfma_f32_16x16x32_bf16 v[46:49], v[152:155], v[216:219], v[46:49]
	v_mfma_f32_16x16x32_bf16 v[42:45], v[160:163], v[216:219], v[42:45]
	v_mfma_f32_16x16x32_bf16 v[30:33], v[152:155], v[224:227], v[30:33]
	v_mfma_f32_16x16x32_bf16 v[26:29], v[160:163], v[224:227], v[26:29]
	v_mfma_f32_16x16x32_bf16 v[14:17], v[152:155], v[232:235], v[14:17]
	v_mfma_f32_16x16x32_bf16 v[10:13], v[160:163], v[232:235], v[10:13]
	s_cmp_lt_u32 s82, s59
	s_cselect_b32 s83, 0x80, 0
	s_add_u32 s76, s76, s83
	s_addc_u32 s77, s77, 0
	s_add_u32 vcc_lo, vcc_lo, s83
	s_addc_u32 vcc_hi, vcc_hi, 0
	s_add_i32 s82, s82, 1
	s_setprio 0
	s_barrier
	v_add_u32_e32 v136, 0x18000, v147
	ds_read_b128 v[148:151], v136
	ds_read_b128 v[152:155], v136 offset:1024
	ds_read_b128 v[156:159], v136 offset:2048
	ds_read_b128 v[160:163], v136 offset:3072
	ds_read_b128 v[202:205], v165 offset:49152
	ds_read_b128 v[208:211], v165 offset:50176
	ds_read_b128 v[212:215], v165 offset:51200
	ds_read_b128 v[216:219], v165 offset:52224
	ds_read_b128 v[220:223], v165 offset:53248
	ds_read_b128 v[224:227], v165 offset:54272
	ds_read_b128 v[228:231], v165 offset:55296
	ds_read_b128 v[232:235], v165 offset:56320
	v_lshl_add_u64 v[136:137], s[76:77], 0, v[0:1]
	s_add_i32 m0, s94, 0x4000
	v_lshl_add_u64 v[144:145], s[76:77], 0, v[130:131]
	global_load_lds_dwordx4 v[136:137], off
	s_add_i32 m0, s94, 0x6000
	s_nop 0
	global_load_lds_dwordx4 v[144:145], off
	s_waitcnt vmcnt(6)
	s_waitcnt lgkmcnt(0)
	s_barrier
	s_setprio 1
	v_mfma_f32_16x16x32_bf16 v[62:65], v[148:151], v[202:205], v[62:65]
	v_mfma_f32_16x16x32_bf16 v[58:61], v[156:159], v[202:205], v[58:61]
	v_mfma_f32_16x16x32_bf16 v[46:49], v[148:151], v[212:215], v[46:49]
	v_lshl_add_u64 v[182:183], vcc, 0, v[0:1]
	s_add_i32 m0, s93, 0x10000
	v_lshl_add_u64 v[236:237], vcc, 0, v[130:131]
	global_load_lds_dwordx4 v[182:183], off
	v_mfma_f32_16x16x32_bf16 v[42:45], v[156:159], v[212:215], v[42:45]
	v_mfma_f32_16x16x32_bf16 v[30:33], v[148:151], v[220:223], v[30:33]
	v_mfma_f32_16x16x32_bf16 v[26:29], v[156:159], v[220:223], v[26:29]
	v_mfma_f32_16x16x32_bf16 v[14:17], v[148:151], v[228:231], v[14:17]
	v_mfma_f32_16x16x32_bf16 v[10:13], v[156:159], v[228:231], v[10:13]
	v_mfma_f32_16x16x32_bf16 v[62:65], v[152:155], v[208:211], v[62:65]
	s_add_i32 m0, s93, 0x12000
	s_nop 0
	global_load_lds_dwordx4 v[236:237], off
	v_mfma_f32_16x16x32_bf16 v[58:61], v[160:163], v[208:211], v[58:61]
	v_mfma_f32_16x16x32_bf16 v[46:49], v[152:155], v[216:219], v[46:49]
	v_mfma_f32_16x16x32_bf16 v[42:45], v[160:163], v[216:219], v[42:45]
	v_mfma_f32_16x16x32_bf16 v[30:33], v[152:155], v[224:227], v[30:33]
	v_mfma_f32_16x16x32_bf16 v[26:29], v[160:163], v[224:227], v[26:29]
	v_mfma_f32_16x16x32_bf16 v[14:17], v[152:155], v[232:235], v[14:17]
	v_mfma_f32_16x16x32_bf16 v[10:13], v[160:163], v[232:235], v[10:13]
	s_cmp_lt_u32 s82, s59
	s_cselect_b32 s83, 0x80, 0
	s_add_u32 s76, s76, s83
	s_addc_u32 s77, s77, 0
	s_add_u32 vcc_lo, vcc_lo, s83
	s_addc_u32 vcc_hi, vcc_hi, 0
	s_add_i32 s82, s82, 1
	s_setprio 0
	s_barrier
; #define PG8_STAGE(bufoff, gbase, voff) do { _Pragma("unroll") for (int _i = 0; _i < 2; ++_i) \
;         __builtin_amdgcn_global_load_lds((const unsigned*)((const char*)(gbase) + (voff)[_i]), (PG8_LAS unsigned*)(lds + (bufoff) + ldsw + _i * 8192), 16, 0, 0); } while (0)
; #define PG8_LDA(dst, b, h) do { _Pragma("unroll") for (int m = 0; m < 4; ++m) _Pragma("unroll") for (int k = 0; k < 2; ++k) dst[m][k] = *(const PG8_LAS bf16x8*)(lds + PG8_SA(b, h) + aoff + m * 2048 + k * 1024); } while (0)
; #define PG8_LDB(dst, b, h) do { _Pragma("unroll") for (int n = 0; n < 2; ++n) _Pragma("unroll") for (int k = 0; k < 2; ++k) dst[n][k] = *(const PG8_LAS bf16x8*)(lds + PG8_SB(b, h) + boff + n * 2048 + k * 1024); } while (0)
; #define PG8_MMA(ai, bj, At, Bt) do { __builtin_amdgcn_s_setprio(1); _Pragma("unroll") for (int m = 0; m < 4; ++m) _Pragma("unroll") for (int n = 0; n < 2; ++n) _Pragma("unroll") for (int k = 0; k < 2; ++k) \
;         acc[ai][bj][m][n] = __builtin_amdgcn_mfma_f32_16x16x32_bf16(Bt[n][k], At[m][k], acc[ai][bj][m][n], 0, 0, 0); __builtin_amdgcn_s_setprio(0); } while (0)
; #define PG8_WAIT_V(n) asm volatile("s_waitcnt vmcnt(" #n ")" ::: "memory")
; template <class Epi, class Sched, bool ALIGN_EPI = false, bool SP2 = false>
; __device__ __forceinline__ void gemm_phase(PG8_LAS unsigned char* lds, const Gemm g, const Sched& S, const Epi& E) {
;     ...
;             PG8_LDB(B0, 0, 0); PG8_LDB(B1, 0, 1); PG8_SCHED; PG8_LDA(At, 0, 0); PG8_STAGE(PG8_SA(1, 1), a1 + hstep, voffA);
;             PG8_WAIT_V(8); PG8_WAIT_L(0); PG8_BAR; PG8_MMA(0, 0, At, B0); PG8_MMA(0, 1, At, B1); PG8_BAR; PG8_SCHED;
;             PG8_LDA(At, 0, 1); PG8_STAGE(PG8_SB(0, 0), b2, voffB); PG8_STAGE(PG8_SB(0, 1), b2 + hstep, voffB); PG8_STAGE(PG8_SA(0, 0), a2, voffA);
;             PG8_WAIT_V(8); PG8_WAIT_L(0); PG8_BAR; PG8_MMA(1, 0, At, B0); PG8_MMA(1, 1, At, B1); PG8_BAR; PG8_SCHED;
;             PG8_LDB(B0, 1, 0); PG8_LDB(B1, 1, 1); PG8_SCHED; PG8_LDA(At, 1, 0); PG8_STAGE(PG8_SA(0, 1), a2 + hstep, voffA);
;             PG8_WAIT_V(8); PG8_WAIT_L(0); PG8_BAR; PG8_MMA(0, 0, At, B0); PG8_MMA(0, 1, At, B1); PG8_BAR; PG8_SCHED;
;             PG8_LDA(At, 1, 1); PG8_STAGE(PG8_SB(1, 0), b3, voffB); PG8_STAGE(PG8_SB(1, 1), b3 + hstep, voffB); PG8_STAGE(PG8_SA(1, 0), a3, voffA);
;             PG8_WAIT_V(8); PG8_WAIT_L(0); PG8_BAR; PG8_MMA(1, 0, At, B0); PG8_MMA(1, 1, At, B1); PG8_BAR; PG8_SCHED;
	v_add_u32_e32 v136, 0x14000, v147
	ds_read_b128 v[148:151], v136
	ds_read_b128 v[152:155], v136 offset:1024
	ds_read_b128 v[156:159], v136 offset:2048
	ds_read_b128 v[160:163], v136 offset:3072
	ds_read_b128 v[202:205], v165
	ds_read_b128 v[208:211], v165 offset:1024
	ds_read_b128 v[212:215], v165 offset:2048
	ds_read_b128 v[216:219], v165 offset:3072
	ds_read_b128 v[220:223], v165 offset:4096
	ds_read_b128 v[224:227], v165 offset:5120
	ds_read_b128 v[228:231], v165 offset:6144
	ds_read_b128 v[232:235], v165 offset:7168
	v_lshl_add_u64 v[136:137], s[76:77], 0, v[0:1]
	s_add_i32 m0, s94, 0xc000
	v_lshl_add_u64 v[144:145], s[76:77], 0, v[130:131]
	global_load_lds_dwordx4 v[136:137], off
	s_add_i32 m0, s94, 0xe000
	s_nop 0
	global_load_lds_dwordx4 v[144:145], off
	s_waitcnt vmcnt(6)
	s_waitcnt lgkmcnt(0)
	s_barrier
	s_setprio 1
	v_mfma_f32_16x16x32_bf16 v[62:65], v[148:151], v[202:205], v[62:65]
	v_mfma_f32_16x16x32_bf16 v[58:61], v[156:159], v[202:205], v[58:61]
	v_mfma_f32_16x16x32_bf16 v[46:49], v[148:151], v[212:215], v[46:49]
	v_lshl_add_u64 v[182:183], vcc, 0, v[0:1]
	s_add_i32 m0, s93, 0x18000
	v_lshl_add_u64 v[236:237], vcc, 0, v[130:131]
	global_load_lds_dwordx4 v[182:183], off
	v_mfma_f32_16x16x32_bf16 v[42:45], v[156:159], v[212:215], v[42:45]
	v_mfma_f32_16x16x32_bf16 v[30:33], v[148:151], v[220:223], v[30:33]
	v_mfma_f32_16x16x32_bf16 v[26:29], v[156:159], v[220:223], v[26:29]
	v_mfma_f32_16x16x32_bf16 v[14:17], v[148:151], v[228:231], v[14:17]
	v_mfma_f32_16x16x32_bf16 v[10:13], v[156:159], v[228:231], v[10:13]
	v_mfma_f32_16x16x32_bf16 v[62:65], v[152:155], v[208:211], v[62:65]
	s_add_i32 m0, s93, 0x1a000
	s_nop 0
	global_load_lds_dwordx4 v[236:237], off
	v_mfma_f32_16x16x32_bf16 v[58:61], v[160:163], v[208:211], v[58:61]
	v_mfma_f32_16x16x32_bf16 v[46:49], v[152:155], v[216:219], v[46:49]
	v_mfma_f32_16x16x32_bf16 v[42:45], v[160:163], v[216:219], v[42:45]
	v_mfma_f32_16x16x32_bf16 v[30:33], v[152:155], v[224:227], v[30:33]
	v_mfma_f32_16x16x32_bf16 v[26:29], v[160:163], v[224:227], v[26:29]
	v_mfma_f32_16x16x32_bf16 v[14:17], v[152:155], v[232:235], v[14:17]
	v_mfma_f32_16x16x32_bf16 v[10:13], v[160:163], v[232:235], v[10:13]
	s_cmp_lt_u32 s82, s59
	s_cselect_b32 s83, 0x80, 0
	s_add_u32 s76, s76, s83
	s_addc_u32 s77, s77, 0
	s_add_u32 vcc_lo, vcc_lo, s83
	s_addc_u32 vcc_hi, vcc_hi, 0
	s_add_i32 s82, s82, 1
	s_setprio 0
	s_barrier
	v_add_u32_e32 v136, 0x1c000, v147
	ds_read_b128 v[148:151], v136
	ds_read_b128 v[152:155], v136 offset:1024
	ds_read_b128 v[156:159], v136 offset:2048
	ds_read_b128 v[160:163], v136 offset:3072
	ds_read_b128 v[202:205], v165 offset:32768
	ds_read_b128 v[208:211], v165 offset:33792
	ds_read_b128 v[212:215], v165 offset:34816
	ds_read_b128 v[216:219], v165 offset:35840
	ds_read_b128 v[220:223], v165 offset:36864
	ds_read_b128 v[224:227], v165 offset:37888
	ds_read_b128 v[228:231], v165 offset:38912
	ds_read_b128 v[232:235], v165 offset:39936
	v_lshl_add_u64 v[136:137], s[76:77], 0, v[0:1]
	s_add_i32 m0, s94, 0x0
	v_lshl_add_u64 v[144:145], s[76:77], 0, v[130:131]
	global_load_lds_dwordx4 v[136:137], off
	s_add_i32 m0, s94, 0x2000
	s_nop 0
	global_load_lds_dwordx4 v[144:145], off
	s_waitcnt vmcnt(6)
	s_waitcnt lgkmcnt(0)
	s_barrier
	s_setprio 1
	v_mfma_f32_16x16x32_bf16 v[62:65], v[148:151], v[202:205], v[62:65]
	v_mfma_f32_16x16x32_bf16 v[58:61], v[156:159], v[202:205], v[58:61]
	v_mfma_f32_16x16x32_bf16 v[46:49], v[148:151], v[212:215], v[46:49]
	v_lshl_add_u64 v[182:183], vcc, 0, v[0:1]
	s_add_i32 m0, s93, 0x14000
	v_lshl_add_u64 v[236:237], vcc, 0, v[130:131]
	global_load_lds_dwordx4 v[182:183], off
	v_mfma_f32_16x16x32_bf16 v[42:45], v[156:159], v[212:215], v[42:45]
	v_mfma_f32_16x16x32_bf16 v[30:33], v[148:151], v[220:223], v[30:33]
	v_mfma_f32_16x16x32_bf16 v[26:29], v[156:159], v[220:223], v[26:29]
	v_mfma_f32_16x16x32_bf16 v[14:17], v[148:151], v[228:231], v[14:17]
	v_mfma_f32_16x16x32_bf16 v[10:13], v[156:159], v[228:231], v[10:13]
	v_mfma_f32_16x16x32_bf16 v[62:65], v[152:155], v[208:211], v[62:65]
	s_add_i32 m0, s93, 0x16000
	s_nop 0
	global_load_lds_dwordx4 v[236:237], off
	v_mfma_f32_16x16x32_bf16 v[58:61], v[160:163], v[208:211], v[58:61]
	v_mfma_f32_16x16x32_bf16 v[46:49], v[152:155], v[216:219], v[46:49]
	v_mfma_f32_16x16x32_bf16 v[42:45], v[160:163], v[216:219], v[42:45]
	v_mfma_f32_16x16x32_bf16 v[30:33], v[152:155], v[224:227], v[30:33]
	v_mfma_f32_16x16x32_bf16 v[26:29], v[160:163], v[224:227], v[26:29]
	v_mfma_f32_16x16x32_bf16 v[14:17], v[152:155], v[232:235], v[14:17]
	v_mfma_f32_16x16x32_bf16 v[10:13], v[160:163], v[232:235], v[10:13]
	s_cmp_lt_u32 s82, s59
	s_cselect_b32 s83, 0x80, 0
	s_add_u32 s76, s76, s83
	s_addc_u32 s77, s77, 0
	s_add_u32 vcc_lo, vcc_lo, s83
	s_addc_u32 vcc_hi, vcc_hi, 0
	s_add_i32 s82, s82, 1
	s_setprio 0
	s_barrier
	s_add_i32 s83, s82, -3
	s_cmp_lt_u32 s83, s79
	s_cbranch_scc0 .Lkq_2_post
; #define PG8_STAGE(bufoff, gbase, voff) do { _Pragma("unroll") for (int _i = 0; _i < 2; ++_i) \
;         __builtin_amdgcn_global_load_lds((const unsigned*)((const char*)(gbase) + (voff)[_i]), (PG8_LAS unsigned*)(lds + (bufoff) + ldsw + _i * 8192), 16, 0, 0); } while (0)
; #define PG8_LDA(dst, b, h) do { _Pragma("unroll") for (int m = 0; m < 4; ++m) _Pragma("unroll") for (int k = 0; k < 2; ++k) dst[m][k] = *(const PG8_LAS bf16x8*)(lds + PG8_SA(b, h) + aoff + m * 2048 + k * 1024); } while (0)
; #define PG8_LDB(dst, b, h) do { _Pragma("unroll") for (int n = 0; n < 2; ++n) _Pragma("unroll") for (int k = 0; k < 2; ++k) dst[n][k] = *(const PG8_LAS bf16x8*)(lds + PG8_SB(b, h) + boff + n * 2048 + k * 1024); } while (0)
; #define PG8_MMA(ai, bj, At, Bt) do { __builtin_amdgcn_s_setprio(1); _Pragma("unroll") for (int m = 0; m < 4; ++m) _Pragma("unroll") for (int n = 0; n < 2; ++n) _Pragma("unroll") for (int k = 0; k < 2; ++k) \
;         acc[ai][bj][m][n] = __builtin_amdgcn_mfma_f32_16x16x32_bf16(Bt[n][k], At[m][k], acc[ai][bj][m][n], 0, 0, 0); __builtin_amdgcn_s_setprio(0); } while (0)
; #define PG8_WAIT_V(n) asm volatile("s_waitcnt vmcnt(" #n ")" ::: "memory")
; template <class Epi, class Sched, bool ALIGN_EPI = false, bool SP2 = false>
; __device__ __forceinline__ void gemm_phase(PG8_LAS unsigned char* lds, const Gemm g, const Sched& S, const Epi& E) {
;     ...
;             PG8_LDB(B0, 0, 0); PG8_LDB(B1, 0, 1); PG8_SCHED; PG8_LDA(At, 0, 0); PG8_STAGE(PG8_SA(1, 1), a1 + hstep, voffA);
;             PG8_WAIT_V(8); PG8_WAIT_L(0); PG8_BAR; PG8_MMA(0, 0, At, B0); PG8_MMA(0, 1, At, B1); PG8_BAR; PG8_SCHED;
;             PG8_LDA(At, 0, 1); PG8_STAGE(PG8_SB(0, 0), b2, voffB); PG8_STAGE(PG8_SB(0, 1), b2 + hstep, voffB); PG8_STAGE(PG8_SA(0, 0), a2, voffA);
;             PG8_WAIT_V(8); PG8_WAIT_L(0); PG8_BAR; PG8_MMA(1, 0, At, B0); PG8_MMA(1, 1, At, B1); PG8_BAR; PG8_SCHED;
;             PG8_LDB(B0, 1, 0); PG8_LDB(B1, 1, 1); PG8_SCHED; PG8_LDA(At, 1, 0); PG8_STAGE(PG8_SA(0, 1), a2 + hstep, voffA);
;             PG8_WAIT_V(8); PG8_WAIT_L(0); PG8_BAR; PG8_MMA(0, 0, At, B0); PG8_MMA(0, 1, At, B1); PG8_BAR; PG8_SCHED;
;             PG8_LDA(At, 1, 1); PG8_STAGE(PG8_SB(1, 0), b3, voffB); PG8_STAGE(PG8_SB(1, 1), b3 + hstep, voffB); PG8_STAGE(PG8_SA(1, 0), a3, voffA);
;             PG8_WAIT_V(8); PG8_WAIT_L(0); PG8_BAR; PG8_MMA(1, 0, At, B0); PG8_MMA(1, 1, At, B1); PG8_BAR; PG8_SCHED;
.Lkq_2_loop:
	v_add_u32_e32 v136, 0x10000, v147
	ds_read_b128 v[148:151], v136
	ds_read_b128 v[152:155], v136 offset:1024
	ds_read_b128 v[156:159], v136 offset:2048
	ds_read_b128 v[160:163], v136 offset:3072
	ds_read_b128 v[202:205], v165 offset:16384
	ds_read_b128 v[208:211], v165 offset:17408
	ds_read_b128 v[212:215], v165 offset:18432
	ds_read_b128 v[216:219], v165 offset:19456
	ds_read_b128 v[220:223], v165 offset:20480
	ds_read_b128 v[224:227], v165 offset:21504
	ds_read_b128 v[228:231], v165 offset:22528
	ds_read_b128 v[232:235], v165 offset:23552
	v_lshl_add_u64 v[136:137], s[76:77], 0, v[0:1]
	s_add_i32 m0, s94, 0x8000
	v_lshl_add_u64 v[144:145], s[76:77], 0, v[130:131]
	global_load_lds_dwordx4 v[136:137], off
	s_add_i32 m0, s94, 0xa000
	s_nop 0
	global_load_lds_dwordx4 v[144:145], off
	s_waitcnt vmcnt(6)
	s_waitcnt lgkmcnt(0)
	s_barrier
	s_setprio 1
	v_mfma_f32_16x16x32_bf16 v[62:65], v[148:151], v[202:205], v[62:65]
	v_mfma_f32_16x16x32_bf16 v[58:61], v[156:159], v[202:205], v[58:61]
	v_mfma_f32_16x16x32_bf16 v[46:49], v[148:151], v[212:215], v[46:49]
	v_lshl_add_u64 v[182:183], vcc, 0, v[0:1]
	s_add_i32 m0, s93, 0x1c000
	v_lshl_add_u64 v[236:237], vcc, 0, v[130:131]
	global_load_lds_dwordx4 v[182:183], off
	v_mfma_f32_16x16x32_bf16 v[42:45], v[156:159], v[212:215], v[42:45]
	v_mfma_f32_16x16x32_bf16 v[30:33], v[148:151], v[220:223], v[30:33]
	v_mfma_f32_16x16x32_bf16 v[26:29], v[156:159], v[220:223], v[26:29]
	v_mfma_f32_16x16x32_bf16 v[14:17], v[148:151], v[228:231], v[14:17]
	v_mfma_f32_16x16x32_bf16 v[10:13], v[156:159], v[228:231], v[10:13]
	v_mfma_f32_16x16x32_bf16 v[62:65], v[152:155], v[208:211], v[62:65]
	s_add_i32 m0, s93, 0x1e000
	s_nop 0
	global_load_lds_dwordx4 v[236:237], off
	v_mfma_f32_16x16x32_bf16 v[58:61], v[160:163], v[208:211], v[58:61]
	v_mfma_f32_16x16x32_bf16 v[46:49], v[152:155], v[216:219], v[46:49]
	v_mfma_f32_16x16x32_bf16 v[42:45], v[160:163], v[216:219], v[42:45]
	v_mfma_f32_16x16x32_bf16 v[30:33], v[152:155], v[224:227], v[30:33]
	v_mfma_f32_16x16x32_bf16 v[26:29], v[160:163], v[224:227], v[26:29]
	v_mfma_f32_16x16x32_bf16 v[14:17], v[152:155], v[232:235], v[14:17]
	v_mfma_f32_16x16x32_bf16 v[10:13], v[160:163], v[232:235], v[10:13]
	s_cmp_lt_u32 s82, s59
	s_cselect_b32 s83, 0x80, 0
	s_add_u32 s76, s76, s83
	s_addc_u32 s77, s77, 0
	s_add_u32 vcc_lo, vcc_lo, s83
	s_addc_u32 vcc_hi, vcc_hi, 0
	s_add_i32 s82, s82, 1
	s_setprio 0
	s_barrier
	v_add_u32_e32 v136, 0x18000, v147
	ds_read_b128 v[148:151], v136
	ds_read_b128 v[152:155], v136 offset:1024
	ds_read_b128 v[156:159], v136 offset:2048
	ds_read_b128 v[160:163], v136 offset:3072
	ds_read_b128 v[202:205], v165 offset:49152
	ds_read_b128 v[208:211], v165 offset:50176
	ds_read_b128 v[212:215], v165 offset:51200
	ds_read_b128 v[216:219], v165 offset:52224
	ds_read_b128 v[220:223], v165 offset:53248
	ds_read_b128 v[224:227], v165 offset:54272
	ds_read_b128 v[228:231], v165 offset:55296
	ds_read_b128 v[232:235], v165 offset:56320
	v_lshl_add_u64 v[136:137], s[76:77], 0, v[0:1]
	s_add_i32 m0, s94, 0x4000
	v_lshl_add_u64 v[144:145], s[76:77], 0, v[130:131]
	global_load_lds_dwordx4 v[136:137], off
	s_add_i32 m0, s94, 0x6000
	s_nop 0
	global_load_lds_dwordx4 v[144:145], off
	s_waitcnt vmcnt(6)
	s_waitcnt lgkmcnt(0)
	s_barrier
	s_setprio 1
	v_mfma_f32_16x16x32_bf16 v[62:65], v[148:151], v[202:205], v[62:65]
	v_mfma_f32_16x16x32_bf16 v[58:61], v[156:159], v[202:205], v[58:61]
	v_mfma_f32_16x16x32_bf16 v[46:49], v[148:151], v[212:215], v[46:49]
	v_lshl_add_u64 v[182:183], vcc, 0, v[0:1]
	s_add_i32 m0, s93, 0x10000
	v_lshl_add_u64 v[236:237], vcc, 0, v[130:131]
	global_load_lds_dwordx4 v[182:183], off
	v_mfma_f32_16x16x32_bf16 v[42:45], v[156:159], v[212:215], v[42:45]
	v_mfma_f32_16x16x32_bf16 v[30:33], v[148:151], v[220:223], v[30:33]
	v_mfma_f32_16x16x32_bf16 v[26:29], v[156:159], v[220:223], v[26:29]
	v_mfma_f32_16x16x32_bf16 v[14:17], v[148:151], v[228:231], v[14:17]
	v_mfma_f32_16x16x32_bf16 v[10:13], v[156:159], v[228:231], v[10:13]
	v_mfma_f32_16x16x32_bf16 v[62:65], v[152:155], v[208:211], v[62:65]
	s_add_i32 m0, s93, 0x12000
	s_nop 0
	global_load_lds_dwordx4 v[236:237], off
	v_mfma_f32_16x16x32_bf16 v[58:61], v[160:163], v[208:211], v[58:61]
	v_mfma_f32_16x16x32_bf16 v[46:49], v[152:155], v[216:219], v[46:49]
	v_mfma_f32_16x16x32_bf16 v[42:45], v[160:163], v[216:219], v[42:45]
	v_mfma_f32_16x16x32_bf16 v[30:33], v[152:155], v[224:227], v[30:33]
	v_mfma_f32_16x16x32_bf16 v[26:29], v[160:163], v[224:227], v[26:29]
	v_mfma_f32_16x16x32_bf16 v[14:17], v[152:155], v[232:235], v[14:17]
	v_mfma_f32_16x16x32_bf16 v[10:13], v[160:163], v[232:235], v[10:13]
	s_cmp_lt_u32 s82, s59
	s_cselect_b32 s83, 0x80, 0
	s_add_u32 s76, s76, s83
	s_addc_u32 s77, s77, 0
	s_add_u32 vcc_lo, vcc_lo, s83
	s_addc_u32 vcc_hi, vcc_hi, 0
	s_add_i32 s82, s82, 1
	s_setprio 0
	s_barrier
; #define PG8_STAGE(bufoff, gbase, voff) do { _Pragma("unroll") for (int _i = 0; _i < 2; ++_i) \
;         __builtin_amdgcn_global_load_lds((const unsigned*)((const char*)(gbase) + (voff)[_i]), (PG8_LAS unsigned*)(lds + (bufoff) + ldsw + _i * 8192), 16, 0, 0); } while (0)
; #define PG8_LDA(dst, b, h) do { _Pragma("unroll") for (int m = 0; m < 4; ++m) _Pragma("unroll") for (int k = 0; k < 2; ++k) dst[m][k] = *(const PG8_LAS bf16x8*)(lds + PG8_SA(b, h) + aoff + m * 2048 + k * 1024); } while (0)
; #define PG8_LDB(dst, b, h) do { _Pragma("unroll") for (int n = 0; n < 2; ++n) _Pragma("unroll") for (int k = 0; k < 2; ++k) dst[n][k] = *(const PG8_LAS bf16x8*)(lds + PG8_SB(b, h) + boff + n * 2048 + k * 1024); } while (0)
; #define PG8_MMA(ai, bj, At, Bt) do { __builtin_amdgcn_s_setprio(1); _Pragma("unroll") for (int m = 0; m < 4; ++m) _Pragma("unroll") for (int n = 0; n < 2; ++n) _Pragma("unroll") for (int k = 0; k < 2; ++k) \
;         acc[ai][bj][m][n] = __builtin_amdgcn_mfma_f32_16x16x32_bf16(Bt[n][k], At[m][k], acc[ai][bj][m][n], 0, 0, 0); __builtin_amdgcn_s_setprio(0); } while (0)
; #define PG8_WAIT_V(n) asm volatile("s_waitcnt vmcnt(" #n ")" ::: "memory")
; template <class Epi, class Sched, bool ALIGN_EPI = false, bool SP2 = false>
; __device__ __forceinline__ void gemm_phase(PG8_LAS unsigned char* lds, const Gemm g, const Sched& S, const Epi& E) {
;     ...
;             PG8_LDB(B0, 0, 0); PG8_LDB(B1, 0, 1); PG8_SCHED; PG8_LDA(At, 0, 0); PG8_STAGE(PG8_SA(1, 1), a1 + hstep, voffA);
;             PG8_WAIT_V(8); PG8_WAIT_L(0); PG8_BAR; PG8_MMA(0, 0, At, B0); PG8_MMA(0, 1, At, B1); PG8_BAR; PG8_SCHED;
;             PG8_LDA(At, 0, 1); PG8_STAGE(PG8_SB(0, 0), b2, voffB); PG8_STAGE(PG8_SB(0, 1), b2 + hstep, voffB); PG8_STAGE(PG8_SA(0, 0), a2, voffA);
;             PG8_WAIT_V(8); PG8_WAIT_L(0); PG8_BAR; PG8_MMA(1, 0, At, B0); PG8_MMA(1, 1, At, B1); PG8_BAR; PG8_SCHED;
;             PG8_LDB(B0, 1, 0); PG8_LDB(B1, 1, 1); PG8_SCHED; PG8_LDA(At, 1, 0); PG8_STAGE(PG8_SA(0, 1), a2 + hstep, voffA);
;             PG8_WAIT_V(8); PG8_WAIT_L(0); PG8_BAR; PG8_MMA(0, 0, At, B0); PG8_MMA(0, 1, At, B1); PG8_BAR; PG8_SCHED;
;             PG8_LDA(At, 1, 1); PG8_STAGE(PG8_SB(1, 0), b3, voffB); PG8_STAGE(PG8_SB(1, 1), b3 + hstep, voffB); PG8_STAGE(PG8_SA(1, 0), a3, voffA);
;             PG8_WAIT_V(8); PG8_WAIT_L(0); PG8_BAR; PG8_MMA(1, 0, At, B0); PG8_MMA(1, 1, At, B1); PG8_BAR; PG8_SCHED;
	v_add_u32_e32 v136, 0x14000, v147
	ds_read_b128 v[148:151], v136
	ds_read_b128 v[152:155], v136 offset:1024
	ds_read_b128 v[156:159], v136 offset:2048
	ds_read_b128 v[160:163], v136 offset:3072
	ds_read_b128 v[202:205], v165
	ds_read_b128 v[208:211], v165 offset:1024
	ds_read_b128 v[212:215], v165 offset:2048
	ds_read_b128 v[216:219], v165 offset:3072
	ds_read_b128 v[220:223], v165 offset:4096
	ds_read_b128 v[224:227], v165 offset:5120
	ds_read_b128 v[228:231], v165 offset:6144
	ds_read_b128 v[232:235], v165 offset:7168
	v_lshl_add_u64 v[136:137], s[76:77], 0, v[0:1]
	s_add_i32 m0, s94, 0xc000
	v_lshl_add_u64 v[144:145], s[76:77], 0, v[130:131]
	global_load_lds_dwordx4 v[136:137], off
	s_add_i32 m0, s94, 0xe000
	s_nop 0
	global_load_lds_dwordx4 v[144:145], off
	s_waitcnt vmcnt(6)
	s_waitcnt lgkmcnt(0)
	s_barrier
	s_setprio 1
	v_mfma_f32_16x16x32_bf16 v[62:65], v[148:151], v[202:205], v[62:65]
	v_mfma_f32_16x16x32_bf16 v[58:61], v[156:159], v[202:205], v[58:61]
	v_mfma_f32_16x16x32_bf16 v[46:49], v[148:151], v[212:215], v[46:49]
	v_lshl_add_u64 v[182:183], vcc, 0, v[0:1]
	s_add_i32 m0, s93, 0x18000
	v_lshl_add_u64 v[236:237], vcc, 0, v[130:131]
	global_load_lds_dwordx4 v[182:183], off
	v_mfma_f32_16x16x32_bf16 v[42:45], v[156:159], v[212:215], v[42:45]
	v_mfma_f32_16x16x32_bf16 v[30:33], v[148:151], v[220:223], v[30:33]
	v_mfma_f32_16x16x32_bf16 v[26:29], v[156:159], v[220:223], v[26:29]
	v_mfma_f32_16x16x32_bf16 v[14:17], v[148:151], v[228:231], v[14:17]
	v_mfma_f32_16x16x32_bf16 v[10:13], v[156:159], v[228:231], v[10:13]
	v_mfma_f32_16x16x32_bf16 v[62:65], v[152:155], v[208:211], v[62:65]
	s_add_i32 m0, s93, 0x1a000
	s_nop 0
	global_load_lds_dwordx4 v[236:237], off
	v_mfma_f32_16x16x32_bf16 v[58:61], v[160:163], v[208:211], v[58:61]
	v_mfma_f32_16x16x32_bf16 v[46:49], v[152:155], v[216:219], v[46:49]
	v_mfma_f32_16x16x32_bf16 v[42:45], v[160:163], v[216:219], v[42:45]
	v_mfma_f32_16x16x32_bf16 v[30:33], v[152:155], v[224:227], v[30:33]
	v_mfma_f32_16x16x32_bf16 v[26:29], v[160:163], v[224:227], v[26:29]
	v_mfma_f32_16x16x32_bf16 v[14:17], v[152:155], v[232:235], v[14:17]
	v_mfma_f32_16x16x32_bf16 v[10:13], v[160:163], v[232:235], v[10:13]
	s_cmp_lt_u32 s82, s59
	s_cselect_b32 s83, 0x80, 0
	s_add_u32 s76, s76, s83
	s_addc_u32 s77, s77, 0
	s_add_u32 vcc_lo, vcc_lo, s83
	s_addc_u32 vcc_hi, vcc_hi, 0
	s_add_i32 s82, s82, 1
	s_setprio 0
	s_barrier
	v_add_u32_e32 v136, 0x1c000, v147
	ds_read_b128 v[148:151], v136
	ds_read_b128 v[152:155], v136 offset:1024
	ds_read_b128 v[156:159], v136 offset:2048
	ds_read_b128 v[160:163], v136 offset:3072
	ds_read_b128 v[202:205], v165 offset:32768
	ds_read_b128 v[208:211], v165 offset:33792
	ds_read_b128 v[212:215], v165 offset:34816
	ds_read_b128 v[216:219], v165 offset:35840
	ds_read_b128 v[220:223], v165 offset:36864
	ds_read_b128 v[224:227], v165 offset:37888
	ds_read_b128 v[228:231], v165 offset:38912
	ds_read_b128 v[232:235], v165 offset:39936
	v_lshl_add_u64 v[136:137], s[76:77], 0, v[0:1]
	s_add_i32 m0, s94, 0x0
	v_lshl_add_u64 v[144:145], s[76:77], 0, v[130:131]
	global_load_lds_dwordx4 v[136:137], off
	s_add_i32 m0, s94, 0x2000
	s_nop 0
	global_load_lds_dwordx4 v[144:145], off
	s_waitcnt vmcnt(6)
	s_waitcnt lgkmcnt(0)
	s_barrier
	s_setprio 1
	v_mfma_f32_16x16x32_bf16 v[62:65], v[148:151], v[202:205], v[62:65]
	v_mfma_f32_16x16x32_bf16 v[58:61], v[156:159], v[202:205], v[58:61]
	v_mfma_f32_16x16x32_bf16 v[46:49], v[148:151], v[212:215], v[46:49]
	v_lshl_add_u64 v[182:183], vcc, 0, v[0:1]
	s_add_i32 m0, s93, 0x14000
	v_lshl_add_u64 v[236:237], vcc, 0, v[130:131]
	global_load_lds_dwordx4 v[182:183], off
	v_mfma_f32_16x16x32_bf16 v[42:45], v[156:159], v[212:215], v[42:45]
	v_mfma_f32_16x16x32_bf16 v[30:33], v[148:151], v[220:223], v[30:33]
	v_mfma_f32_16x16x32_bf16 v[26:29], v[156:159], v[220:223], v[26:29]
	v_mfma_f32_16x16x32_bf16 v[14:17], v[148:151], v[228:231], v[14:17]
	v_mfma_f32_16x16x32_bf16 v[10:13], v[156:159], v[228:231], v[10:13]
	v_mfma_f32_16x16x32_bf16 v[62:65], v[152:155], v[208:211], v[62:65]
	s_add_i32 m0, s93, 0x16000
	s_nop 0
	global_load_lds_dwordx4 v[236:237], off
	v_mfma_f32_16x16x32_bf16 v[58:61], v[160:163], v[208:211], v[58:61]
	v_mfma_f32_16x16x32_bf16 v[46:49], v[152:155], v[216:219], v[46:49]
	v_mfma_f32_16x16x32_bf16 v[42:45], v[160:163], v[216:219], v[42:45]
	v_mfma_f32_16x16x32_bf16 v[30:33], v[152:155], v[224:227], v[30:33]
	v_mfma_f32_16x16x32_bf16 v[26:29], v[160:163], v[224:227], v[26:29]
	v_mfma_f32_16x16x32_bf16 v[14:17], v[152:155], v[232:235], v[14:17]
	v_mfma_f32_16x16x32_bf16 v[10:13], v[160:163], v[232:235], v[10:13]
	s_cmp_lt_u32 s82, s59
	s_cselect_b32 s83, 0x80, 0
	s_add_u32 s76, s76, s83
	s_addc_u32 s77, s77, 0
	s_add_u32 vcc_lo, vcc_lo, s83
	s_addc_u32 vcc_hi, vcc_hi, 0
	s_add_i32 s82, s82, 1
	s_setprio 0
	s_barrier
	s_add_i32 s83, s82, -3
	s_cmp_lt_u32 s83, s79
	s_cbranch_scc1 .Lkq_2_loop

; template <class Epi, class Sched, bool ALIGN_EPI = false, bool SP2 = false>
; __device__ __forceinline__ void gemm_phase(PG8_LAS unsigned char* lds, const Gemm g, const Sched& S, const Epi& E) {
;     ...
;         PG8_STAGE(PG8_SB(0, 0), cB, voffB); PG8_STAGE(PG8_SB(0, 1), cB + hstep, voffB); PG8_STAGE(PG8_SA(0, 0), cA, voffA); PG8_STAGE(PG8_SA(0, 1), cA + hstep, voffA);
;         if (wr == 1) PG8_BAR;
;         PG8_WAIT_V(2); PG8_BAR;
;         PG8_STAGE(PG8_SB(1, 0), cB + kstep, voffB); PG8_STAGE(PG8_SA(1, 0), cA + kstep, voffA); PG8_STAGE(PG8_SB(1, 1), cB + hstep + kstep, voffB);
;         PG8_WAIT_V(6); PG8_BAR;
;     } else {
;         PG8_STAGE(PG8_SB(0, 0), cB, voffB); PG8_STAGE(PG8_SA(0, 0), cA, voffA); PG8_STAGE(PG8_SB(0, 1), cB + hstep, voffB); PG8_STAGE(PG8_SA(0, 1), cA + hstep, voffA);
;         if (wr == 1) PG8_BAR;
;         PG8_WAIT_V(4); PG8_BAR;
;         PG8_STAGE(PG8_SB(1, 0), cB + kstep, voffB); PG8_STAGE(PG8_SA(1, 0), cA + kstep, voffA); PG8_STAGE(PG8_SB(1, 1), cB + hstep + kstep, voffB);
;         PG8_WAIT_V(6); PG8_BAR;
;     }
;     for (;;) {
;         const bool has_next = S.next(ui + 1, nxt);
;         const char* nA = has_next ? (const char*)g.A + (size_t)nxt.pm * tstep : cA; const char* nB = has_next ? (const char*)g.Bt + (size_t)nxt.pn * tstep : cB;
;         for (int t = 0; t < nt; t += 2) {
;             const bool last = (t == nt - 2);
;             const char* a1 = cA + (size_t)(t + 1) * kstep;
;             const char* a2 = last ? nA : cA + (size_t)(t + 2) * kstep; const char* b2 = last ? nB : cB + (size_t)(t + 2) * kstep;
;             const char* a3 = a2 + kstep; const char* b3 = b2 + kstep;
;             if (last && has_next) S.a_ready(nxt);
;             if constexpr (SP2) {
;             PG8_LDB(B0, 0, 0); PG8_LDB(B1, 0, 1); PG8_SCHED; PG8_LDA(At, 0, 0); PG8_STAGE(PG8_SA(1, 1), a1 + hstep, voffA);
;             PG8_WAIT_V(8); PG8_WAIT_L(0); PG8_BAR; PG8_MMA(0, 0, At, B0); PG8_MMA(0, 1, At, B1); PG8_BAR; PG8_SCHED;
;             PG8_LDA(At, 0, 1); PG8_STAGE(PG8_SB(0, 0), b2, voffB); PG8_STAGE(PG8_SB(0, 1), b2 + hstep, voffB); PG8_STAGE(PG8_SA(0, 0), a2, voffA);
;             PG8_WAIT_V(8); PG8_WAIT_L(0); PG8_BAR; PG8_MMA(1, 0, At, B0); PG8_MMA(1, 1, At, B1); PG8_BAR; PG8_SCHED;
;             PG8_LDB(B0, 1, 0); PG8_LDB(B1, 1, 1); PG8_SCHED; PG8_LDA(At, 1, 0); PG8_STAGE(PG8_SA(0, 1), a2 + hstep, voffA);
.Lkq_3:
	s_waitcnt vmcnt(0)
	s_barrier
	s_mov_b64 s[76:77], s[48:49]
	s_add_u32 vcc_lo, s80, 0xffffff80
	s_addc_u32 vcc_hi, s81, -1
	s_add_u32 vcc_lo, vcc_lo, s10
	s_addc_u32 vcc_hi, vcc_hi, 0
	s_add_u32 s76, s76, 0x80
	s_addc_u32 s77, s77, 0
	s_add_u32 vcc_lo, vcc_lo, 0x80
	s_addc_u32 vcc_hi, vcc_hi, 0
	v_lshl_add_u64 v[136:137], s[76:77], 0, v[0:1]
	s_add_i32 m0, s94, 0x4000
	v_lshl_add_u64 v[144:145], s[76:77], 0, v[130:131]
	global_load_lds_dwordx4 v[136:137], off
	s_add_i32 m0, s94, 0x6000
	s_nop 0
	global_load_lds_dwordx4 v[144:145], off
	v_lshl_add_u64 v[182:183], vcc, 0, v[0:1]
	s_add_i32 m0, s93, 0x10000
	v_lshl_add_u64 v[236:237], vcc, 0, v[130:131]
	global_load_lds_dwordx4 v[182:183], off
	s_add_i32 m0, s93, 0x12000
	s_nop 0
	global_load_lds_dwordx4 v[236:237], off
	s_add_u32 s76, s76, 0x80
	s_addc_u32 s77, s77, 0
	s_add_u32 vcc_lo, vcc_lo, 0x80
	s_addc_u32 vcc_hi, vcc_hi, 0
	s_mov_b32 s82, 3
	s_add_i32 s59, s79, -1
	v_add_u32_e32 v136, 0x14000, v147
	ds_read_b128 v[166:169], v136
	ds_read_b128 v[170:173], v136 offset:1024
	ds_read_b128 v[174:177], v136 offset:2048
	ds_read_b128 v[178:181], v136 offset:3072
	ds_read_b128 v[202:205], v165
	ds_read_b128 v[208:211], v165 offset:1024
	ds_read_b128 v[212:215], v165 offset:2048
	ds_read_b128 v[216:219], v165 offset:3072
	ds_read_b128 v[220:223], v165 offset:4096
	ds_read_b128 v[224:227], v165 offset:5120
	ds_read_b128 v[228:231], v165 offset:6144
	ds_read_b128 v[232:235], v165 offset:7168
	v_lshl_add_u64 v[136:137], s[76:77], 0, v[0:1]
	s_add_i32 m0, s94, 0xc000
	v_lshl_add_u64 v[144:145], s[76:77], 0, v[130:131]
	global_load_lds_dwordx4 v[136:137], off
	s_add_i32 m0, s94, 0xe000
	s_nop 0
	global_load_lds_dwordx4 v[144:145], off
	s_waitcnt vmcnt(6)
	s_waitcnt lgkmcnt(0)
	s_barrier
	s_setprio 1
	v_mfma_f32_16x16x32_bf16 v[118:121], v[166:169], v[202:205], 0
	v_mfma_f32_16x16x32_bf16 v[114:117], v[174:177], v[202:205], 0
	v_mfma_f32_16x16x32_bf16 v[102:105], v[166:169], v[212:215], 0
	v_lshl_add_u64 v[182:183], vcc, 0, v[0:1]
	s_add_i32 m0, s93, 0x18000
	v_lshl_add_u64 v[236:237], vcc, 0, v[130:131]
	global_load_lds_dwordx4 v[182:183], off
	v_mfma_f32_16x16x32_bf16 v[98:101], v[174:177], v[212:215], 0
	v_mfma_f32_16x16x32_bf16 v[86:89], v[166:169], v[220:223], 0
	v_mfma_f32_16x16x32_bf16 v[82:85], v[174:177], v[220:223], 0
	v_mfma_f32_16x16x32_bf16 v[70:73], v[166:169], v[228:231], 0
	v_mfma_f32_16x16x32_bf16 v[66:69], v[174:177], v[228:231], 0
	v_mfma_f32_16x16x32_bf16 v[118:121], v[170:173], v[208:211], v[118:121]
	s_add_i32 m0, s93, 0x1a000
	s_nop 0
	global_load_lds_dwordx4 v[236:237], off
	v_mfma_f32_16x16x32_bf16 v[114:117], v[178:181], v[208:211], v[114:117]
	v_mfma_f32_16x16x32_bf16 v[102:105], v[170:173], v[216:219], v[102:105]
	v_mfma_f32_16x16x32_bf16 v[98:101], v[178:181], v[216:219], v[98:101]
	v_mfma_f32_16x16x32_bf16 v[86:89], v[170:173], v[224:227], v[86:89]
	v_mfma_f32_16x16x32_bf16 v[82:85], v[178:181], v[224:227], v[82:85]
	v_mfma_f32_16x16x32_bf16 v[70:73], v[170:173], v[232:235], v[70:73]
	v_mfma_f32_16x16x32_bf16 v[66:69], v[178:181], v[232:235], v[66:69]
	s_cmp_lt_u32 s82, s59
	s_cselect_b32 s83, 0x80, 0
	s_add_u32 s76, s76, s83
	s_addc_u32 s77, s77, 0
	s_add_u32 vcc_lo, vcc_lo, s83
	s_addc_u32 vcc_hi, vcc_hi, 0
	s_add_i32 s82, s82, 1
	s_setprio 0
	s_barrier
	v_add_u32_e32 v136, 0x1c000, v147
	ds_read_b128 v[166:169], v136
	ds_read_b128 v[170:173], v136 offset:1024
	ds_read_b128 v[174:177], v136 offset:2048
	ds_read_b128 v[178:181], v136 offset:3072
	ds_read_b128 v[202:205], v165 offset:32768
	ds_read_b128 v[208:211], v165 offset:33792
	ds_read_b128 v[212:215], v165 offset:34816
	ds_read_b128 v[216:219], v165 offset:35840
	ds_read_b128 v[220:223], v165 offset:36864
	ds_read_b128 v[224:227], v165 offset:37888
	ds_read_b128 v[228:231], v165 offset:38912
	ds_read_b128 v[232:235], v165 offset:39936
	v_lshl_add_u64 v[136:137], s[76:77], 0, v[0:1]
	s_add_i32 m0, s94, 0x0
	v_lshl_add_u64 v[144:145], s[76:77], 0, v[130:131]
	global_load_lds_dwordx4 v[136:137], off
	s_add_i32 m0, s94, 0x2000
	s_nop 0
	global_load_lds_dwordx4 v[144:145], off
	s_waitcnt vmcnt(6)
	s_waitcnt lgkmcnt(0)
	s_barrier
	s_setprio 1
	v_mfma_f32_16x16x32_bf16 v[118:121], v[166:169], v[202:205], v[118:121]
	v_mfma_f32_16x16x32_bf16 v[114:117], v[174:177], v[202:205], v[114:117]
	v_mfma_f32_16x16x32_bf16 v[102:105], v[166:169], v[212:215], v[102:105]
	v_lshl_add_u64 v[182:183], vcc, 0, v[0:1]
	s_add_i32 m0, s93, 0x14000
	v_lshl_add_u64 v[236:237], vcc, 0, v[130:131]
	global_load_lds_dwordx4 v[182:183], off
	v_mfma_f32_16x16x32_bf16 v[98:101], v[174:177], v[212:215], v[98:101]
	v_mfma_f32_16x16x32_bf16 v[86:89], v[166:169], v[220:223], v[86:89]
	v_mfma_f32_16x16x32_bf16 v[82:85], v[174:177], v[220:223], v[82:85]
	v_mfma_f32_16x16x32_bf16 v[70:73], v[166:169], v[228:231], v[70:73]
	v_mfma_f32_16x16x32_bf16 v[66:69], v[174:177], v[228:231], v[66:69]
	v_mfma_f32_16x16x32_bf16 v[118:121], v[170:173], v[208:211], v[118:121]
	s_add_i32 m0, s93, 0x16000
	s_nop 0
	global_load_lds_dwordx4 v[236:237], off
	v_mfma_f32_16x16x32_bf16 v[114:117], v[178:181], v[208:211], v[114:117]
	v_mfma_f32_16x16x32_bf16 v[102:105], v[170:173], v[216:219], v[102:105]
	v_mfma_f32_16x16x32_bf16 v[98:101], v[178:181], v[216:219], v[98:101]
	v_mfma_f32_16x16x32_bf16 v[86:89], v[170:173], v[224:227], v[86:89]
	v_mfma_f32_16x16x32_bf16 v[82:85], v[178:181], v[224:227], v[82:85]
	v_mfma_f32_16x16x32_bf16 v[70:73], v[170:173], v[232:235], v[70:73]
	v_mfma_f32_16x16x32_bf16 v[66:69], v[178:181], v[232:235], v[66:69]
	s_cmp_lt_u32 s82, s59
	s_cselect_b32 s83, 0x80, 0
	s_add_u32 s76, s76, s83
	s_addc_u32 s77, s77, 0
	s_add_u32 vcc_lo, vcc_lo, s83
	s_addc_u32 vcc_hi, vcc_hi, 0
	s_add_i32 s82, s82, 1
	s_setprio 0
	s_barrier
; #define PG8_STAGE(bufoff, gbase, voff) do { _Pragma("unroll") for (int _i = 0; _i < 2; ++_i) \
;         __builtin_amdgcn_global_load_lds((const unsigned*)((const char*)(gbase) + (voff)[_i]), (PG8_LAS unsigned*)(lds + (bufoff) + ldsw + _i * 8192), 16, 0, 0); } while (0)
; #define PG8_LDA(dst, b, h) do { _Pragma("unroll") for (int m = 0; m < 4; ++m) _Pragma("unroll") for (int k = 0; k < 2; ++k) dst[m][k] = *(const PG8_LAS bf16x8*)(lds + PG8_SA(b, h) + aoff + m * 2048 + k * 1024); } while (0)
; #define PG8_LDB(dst, b, h) do { _Pragma("unroll") for (int n = 0; n < 2; ++n) _Pragma("unroll") for (int k = 0; k < 2; ++k) dst[n][k] = *(const PG8_LAS bf16x8*)(lds + PG8_SB(b, h) + boff + n * 2048 + k * 1024); } while (0)
; #define PG8_MMA(ai, bj, At, Bt) do { __builtin_amdgcn_s_setprio(1); _Pragma("unroll") for (int m = 0; m < 4; ++m) _Pragma("unroll") for (int n = 0; n < 2; ++n) _Pragma("unroll") for (int k = 0; k < 2; ++k) \
;         acc[ai][bj][m][n] = __builtin_amdgcn_mfma_f32_16x16x32_bf16(Bt[n][k], At[m][k], acc[ai][bj][m][n], 0, 0, 0); __builtin_amdgcn_s_setprio(0); } while (0)
; #define PG8_WAIT_V(n) asm volatile("s_waitcnt vmcnt(" #n ")" ::: "memory")
; template <class Epi, class Sched, bool ALIGN_EPI = false, bool SP2 = false>
; __device__ __forceinline__ void gemm_phase(PG8_LAS unsigned char* lds, const Gemm g, const Sched& S, const Epi& E) {
;     ...
;             PG8_LDB(B0, 0, 0); PG8_LDB(B1, 0, 1); PG8_SCHED; PG8_LDA(At, 0, 0); PG8_STAGE(PG8_SA(1, 1), a1 + hstep, voffA);
;             PG8_WAIT_V(8); PG8_WAIT_L(0); PG8_BAR; PG8_MMA(0, 0, At, B0); PG8_MMA(0, 1, At, B1); PG8_BAR; PG8_SCHED;
;             PG8_LDA(At, 0, 1); PG8_STAGE(PG8_SB(0, 0), b2, voffB); PG8_STAGE(PG8_SB(0, 1), b2 + hstep, voffB); PG8_STAGE(PG8_SA(0, 0), a2, voffA);
;             PG8_WAIT_V(8); PG8_WAIT_L(0); PG8_BAR; PG8_MMA(1, 0, At, B0); PG8_MMA(1, 1, At, B1); PG8_BAR; PG8_SCHED;
;             PG8_LDB(B0, 1, 0); PG8_LDB(B1, 1, 1); PG8_SCHED; PG8_LDA(At, 1, 0); PG8_STAGE(PG8_SA(0, 1), a2 + hstep, voffA);
;             PG8_WAIT_V(8); PG8_WAIT_L(0); PG8_BAR; PG8_MMA(0, 0, At, B0); PG8_MMA(0, 1, At, B1); PG8_BAR; PG8_SCHED;
;             PG8_LDA(At, 1, 1); PG8_STAGE(PG8_SB(1, 0), b3, voffB); PG8_STAGE(PG8_SB(1, 1), b3 + hstep, voffB); PG8_STAGE(PG8_SA(1, 0), a3, voffA);
;             PG8_WAIT_V(8); PG8_WAIT_L(0); PG8_BAR; PG8_MMA(1, 0, At, B0); PG8_MMA(1, 1, At, B1); PG8_BAR; PG8_SCHED;
	v_add_u32_e32 v136, 0x10000, v147
	ds_read_b128 v[166:169], v136
	ds_read_b128 v[170:173], v136 offset:1024
	ds_read_b128 v[174:177], v136 offset:2048
	ds_read_b128 v[178:181], v136 offset:3072
	ds_read_b128 v[202:205], v165 offset:16384
	ds_read_b128 v[208:211], v165 offset:17408
	ds_read_b128 v[212:215], v165 offset:18432
	ds_read_b128 v[216:219], v165 offset:19456
	ds_read_b128 v[220:223], v165 offset:20480
	ds_read_b128 v[224:227], v165 offset:21504
	ds_read_b128 v[228:231], v165 offset:22528
	ds_read_b128 v[232:235], v165 offset:23552
	v_lshl_add_u64 v[136:137], s[76:77], 0, v[0:1]
	s_add_i32 m0, s94, 0x8000
	v_lshl_add_u64 v[144:145], s[76:77], 0, v[130:131]
	global_load_lds_dwordx4 v[136:137], off
	s_add_i32 m0, s94, 0xa000
	s_nop 0
	global_load_lds_dwordx4 v[144:145], off
	s_waitcnt vmcnt(6)
	s_waitcnt lgkmcnt(0)
	s_barrier
	s_setprio 1
	v_mfma_f32_16x16x32_bf16 v[118:121], v[166:169], v[202:205], v[118:121]
	v_mfma_f32_16x16x32_bf16 v[114:117], v[174:177], v[202:205], v[114:117]
	v_mfma_f32_16x16x32_bf16 v[102:105], v[166:169], v[212:215], v[102:105]
	v_lshl_add_u64 v[182:183], vcc, 0, v[0:1]
	s_add_i32 m0, s93, 0x1c000
	v_lshl_add_u64 v[236:237], vcc, 0, v[130:131]
	global_load_lds_dwordx4 v[182:183], off
	v_mfma_f32_16x16x32_bf16 v[98:101], v[174:177], v[212:215], v[98:101]
	v_mfma_f32_16x16x32_bf16 v[86:89], v[166:169], v[220:223], v[86:89]
	v_mfma_f32_16x16x32_bf16 v[82:85], v[174:177], v[220:223], v[82:85]
	v_mfma_f32_16x16x32_bf16 v[70:73], v[166:169], v[228:231], v[70:73]
	v_mfma_f32_16x16x32_bf16 v[66:69], v[174:177], v[228:231], v[66:69]
	v_mfma_f32_16x16x32_bf16 v[118:121], v[170:173], v[208:211], v[118:121]
	s_add_i32 m0, s93, 0x1e000
	s_nop 0
	global_load_lds_dwordx4 v[236:237], off
	v_mfma_f32_16x16x32_bf16 v[114:117], v[178:181], v[208:211], v[114:117]
	v_mfma_f32_16x16x32_bf16 v[102:105], v[170:173], v[216:219], v[102:105]
	v_mfma_f32_16x16x32_bf16 v[98:101], v[178:181], v[216:219], v[98:101]
	v_mfma_f32_16x16x32_bf16 v[86:89], v[170:173], v[224:227], v[86:89]
	v_mfma_f32_16x16x32_bf16 v[82:85], v[178:181], v[224:227], v[82:85]
	v_mfma_f32_16x16x32_bf16 v[70:73], v[170:173], v[232:235], v[70:73]
	v_mfma_f32_16x16x32_bf16 v[66:69], v[178:181], v[232:235], v[66:69]
	s_cmp_lt_u32 s82, s59
	s_cselect_b32 s83, 0x80, 0
	s_add_u32 s76, s76, s83
	s_addc_u32 s77, s77, 0
	s_add_u32 vcc_lo, vcc_lo, s83
	s_addc_u32 vcc_hi, vcc_hi, 0
	s_add_i32 s82, s82, 1
	s_setprio 0
	s_barrier
	v_add_u32_e32 v136, 0x18000, v147
	ds_read_b128 v[166:169], v136
	ds_read_b128 v[170:173], v136 offset:1024
	ds_read_b128 v[174:177], v136 offset:2048
	ds_read_b128 v[178:181], v136 offset:3072
	ds_read_b128 v[202:205], v165 offset:49152
	ds_read_b128 v[208:211], v165 offset:50176
	ds_read_b128 v[212:215], v165 offset:51200
	ds_read_b128 v[216:219], v165 offset:52224
	ds_read_b128 v[220:223], v165 offset:53248
	ds_read_b128 v[224:227], v165 offset:54272
	ds_read_b128 v[228:231], v165 offset:55296
	ds_read_b128 v[232:235], v165 offset:56320
	v_lshl_add_u64 v[136:137], s[76:77], 0, v[0:1]
	s_add_i32 m0, s94, 0x4000
	v_lshl_add_u64 v[144:145], s[76:77], 0, v[130:131]
	global_load_lds_dwordx4 v[136:137], off
	s_add_i32 m0, s94, 0x6000
	s_nop 0
	global_load_lds_dwordx4 v[144:145], off
	s_waitcnt vmcnt(6)
	s_waitcnt lgkmcnt(0)
	s_barrier
	s_setprio 1
	v_mfma_f32_16x16x32_bf16 v[118:121], v[166:169], v[202:205], v[118:121]
	v_mfma_f32_16x16x32_bf16 v[114:117], v[174:177], v[202:205], v[114:117]
	v_mfma_f32_16x16x32_bf16 v[102:105], v[166:169], v[212:215], v[102:105]
	v_lshl_add_u64 v[182:183], vcc, 0, v[0:1]
	s_add_i32 m0, s93, 0x10000
	v_lshl_add_u64 v[236:237], vcc, 0, v[130:131]
	global_load_lds_dwordx4 v[182:183], off
	v_mfma_f32_16x16x32_bf16 v[98:101], v[174:177], v[212:215], v[98:101]
	v_mfma_f32_16x16x32_bf16 v[86:89], v[166:169], v[220:223], v[86:89]
	v_mfma_f32_16x16x32_bf16 v[82:85], v[174:177], v[220:223], v[82:85]
	v_mfma_f32_16x16x32_bf16 v[70:73], v[166:169], v[228:231], v[70:73]
	v_mfma_f32_16x16x32_bf16 v[66:69], v[174:177], v[228:231], v[66:69]
	v_mfma_f32_16x16x32_bf16 v[118:121], v[170:173], v[208:211], v[118:121]
	s_add_i32 m0, s93, 0x12000
	s_nop 0
	global_load_lds_dwordx4 v[236:237], off
	v_mfma_f32_16x16x32_bf16 v[114:117], v[178:181], v[208:211], v[114:117]
	v_mfma_f32_16x16x32_bf16 v[102:105], v[170:173], v[216:219], v[102:105]
	v_mfma_f32_16x16x32_bf16 v[98:101], v[178:181], v[216:219], v[98:101]
	v_mfma_f32_16x16x32_bf16 v[86:89], v[170:173], v[224:227], v[86:89]
	v_mfma_f32_16x16x32_bf16 v[82:85], v[178:181], v[224:227], v[82:85]
	v_mfma_f32_16x16x32_bf16 v[70:73], v[170:173], v[232:235], v[70:73]
	v_mfma_f32_16x16x32_bf16 v[66:69], v[178:181], v[232:235], v[66:69]
	s_cmp_lt_u32 s82, s59
	s_cselect_b32 s83, 0x80, 0
	s_add_u32 s76, s76, s83
	s_addc_u32 s77, s77, 0
	s_add_u32 vcc_lo, vcc_lo, s83
	s_addc_u32 vcc_hi, vcc_hi, 0
	s_add_i32 s82, s82, 1
	s_setprio 0
	s_barrier
	s_add_i32 s83, s82, -3
	s_cmp_lt_u32 s83, s79
	s_cbranch_scc0 .Lkq_3_post
; #define PG8_STAGE(bufoff, gbase, voff) do { _Pragma("unroll") for (int _i = 0; _i < 2; ++_i) \
;         __builtin_amdgcn_global_load_lds((const unsigned*)((const char*)(gbase) + (voff)[_i]), (PG8_LAS unsigned*)(lds + (bufoff) + ldsw + _i * 8192), 16, 0, 0); } while (0)
; #define PG8_LDA(dst, b, h) do { _Pragma("unroll") for (int m = 0; m < 4; ++m) _Pragma("unroll") for (int k = 0; k < 2; ++k) dst[m][k] = *(const PG8_LAS bf16x8*)(lds + PG8_SA(b, h) + aoff + m * 2048 + k * 1024); } while (0)
; #define PG8_LDB(dst, b, h) do { _Pragma("unroll") for (int n = 0; n < 2; ++n) _Pragma("unroll") for (int k = 0; k < 2; ++k) dst[n][k] = *(const PG8_LAS bf16x8*)(lds + PG8_SB(b, h) + boff + n * 2048 + k * 1024); } while (0)
; #define PG8_MMA(ai, bj, At, Bt) do { __builtin_amdgcn_s_setprio(1); _Pragma("unroll") for (int m = 0; m < 4; ++m) _Pragma("unroll") for (int n = 0; n < 2; ++n) _Pragma("unroll") for (int k = 0; k < 2; ++k) \
;         acc[ai][bj][m][n] = __builtin_amdgcn_mfma_f32_16x16x32_bf16(Bt[n][k], At[m][k], acc[ai][bj][m][n], 0, 0, 0); __builtin_amdgcn_s_setprio(0); } while (0)
; #define PG8_WAIT_V(n) asm volatile("s_waitcnt vmcnt(" #n ")" ::: "memory")
; template <class Epi, class Sched, bool ALIGN_EPI = false, bool SP2 = false>
; __device__ __forceinline__ void gemm_phase(PG8_LAS unsigned char* lds, const Gemm g, const Sched& S, const Epi& E) {
;     ...
;             PG8_LDB(B0, 0, 0); PG8_LDB(B1, 0, 1); PG8_SCHED; PG8_LDA(At, 0, 0); PG8_STAGE(PG8_SA(1, 1), a1 + hstep, voffA);
;             PG8_WAIT_V(8); PG8_WAIT_L(0); PG8_BAR; PG8_MMA(0, 0, At, B0); PG8_MMA(0, 1, At, B1); PG8_BAR; PG8_SCHED;
;             PG8_LDA(At, 0, 1); PG8_STAGE(PG8_SB(0, 0), b2, voffB); PG8_STAGE(PG8_SB(0, 1), b2 + hstep, voffB); PG8_STAGE(PG8_SA(0, 0), a2, voffA);
;             PG8_WAIT_V(8); PG8_WAIT_L(0); PG8_BAR; PG8_MMA(1, 0, At, B0); PG8_MMA(1, 1, At, B1); PG8_BAR; PG8_SCHED;
;             PG8_LDB(B0, 1, 0); PG8_LDB(B1, 1, 1); PG8_SCHED; PG8_LDA(At, 1, 0); PG8_STAGE(PG8_SA(0, 1), a2 + hstep, voffA);
;             PG8_WAIT_V(8); PG8_WAIT_L(0); PG8_BAR; PG8_MMA(0, 0, At, B0); PG8_MMA(0, 1, At, B1); PG8_BAR; PG8_SCHED;
;             PG8_LDA(At, 1, 1); PG8_STAGE(PG8_SB(1, 0), b3, voffB); PG8_STAGE(PG8_SB(1, 1), b3 + hstep, voffB); PG8_STAGE(PG8_SA(1, 0), a3, voffA);
;             PG8_WAIT_V(8); PG8_WAIT_L(0); PG8_BAR; PG8_MMA(1, 0, At, B0); PG8_MMA(1, 1, At, B1); PG8_BAR; PG8_SCHED;
.Lkq_3_loop:
	v_add_u32_e32 v136, 0x14000, v147
	ds_read_b128 v[166:169], v136
	ds_read_b128 v[170:173], v136 offset:1024
	ds_read_b128 v[174:177], v136 offset:2048
	ds_read_b128 v[178:181], v136 offset:3072
	ds_read_b128 v[202:205], v165
	ds_read_b128 v[208:211], v165 offset:1024
	ds_read_b128 v[212:215], v165 offset:2048
	ds_read_b128 v[216:219], v165 offset:3072
	ds_read_b128 v[220:223], v165 offset:4096
	ds_read_b128 v[224:227], v165 offset:5120
	ds_read_b128 v[228:231], v165 offset:6144
	ds_read_b128 v[232:235], v165 offset:7168
	v_lshl_add_u64 v[136:137], s[76:77], 0, v[0:1]
	s_add_i32 m0, s94, 0xc000
	v_lshl_add_u64 v[144:145], s[76:77], 0, v[130:131]
	global_load_lds_dwordx4 v[136:137], off
	s_add_i32 m0, s94, 0xe000
	s_nop 0
	global_load_lds_dwordx4 v[144:145], off
	s_waitcnt vmcnt(6)
	s_waitcnt lgkmcnt(0)
	s_barrier
	s_setprio 1
	v_mfma_f32_16x16x32_bf16 v[118:121], v[166:169], v[202:205], v[118:121]
	v_mfma_f32_16x16x32_bf16 v[114:117], v[174:177], v[202:205], v[114:117]
	v_mfma_f32_16x16x32_bf16 v[102:105], v[166:169], v[212:215], v[102:105]
	v_lshl_add_u64 v[182:183], vcc, 0, v[0:1]
	s_add_i32 m0, s93, 0x18000
	v_lshl_add_u64 v[236:237], vcc, 0, v[130:131]
	global_load_lds_dwordx4 v[182:183], off
	v_mfma_f32_16x16x32_bf16 v[98:101], v[174:177], v[212:215], v[98:101]
	v_mfma_f32_16x16x32_bf16 v[86:89], v[166:169], v[220:223], v[86:89]
	v_mfma_f32_16x16x32_bf16 v[82:85], v[174:177], v[220:223], v[82:85]
	v_mfma_f32_16x16x32_bf16 v[70:73], v[166:169], v[228:231], v[70:73]
	v_mfma_f32_16x16x32_bf16 v[66:69], v[174:177], v[228:231], v[66:69]
	v_mfma_f32_16x16x32_bf16 v[118:121], v[170:173], v[208:211], v[118:121]
	s_add_i32 m0, s93, 0x1a000
	s_nop 0
	global_load_lds_dwordx4 v[236:237], off
	v_mfma_f32_16x16x32_bf16 v[114:117], v[178:181], v[208:211], v[114:117]
	v_mfma_f32_16x16x32_bf16 v[102:105], v[170:173], v[216:219], v[102:105]
	v_mfma_f32_16x16x32_bf16 v[98:101], v[178:181], v[216:219], v[98:101]
	v_mfma_f32_16x16x32_bf16 v[86:89], v[170:173], v[224:227], v[86:89]
	v_mfma_f32_16x16x32_bf16 v[82:85], v[178:181], v[224:227], v[82:85]
	v_mfma_f32_16x16x32_bf16 v[70:73], v[170:173], v[232:235], v[70:73]
	v_mfma_f32_16x16x32_bf16 v[66:69], v[178:181], v[232:235], v[66:69]
	s_cmp_lt_u32 s82, s59
	s_cselect_b32 s83, 0x80, 0
	s_add_u32 s76, s76, s83
	s_addc_u32 s77, s77, 0
	s_add_u32 vcc_lo, vcc_lo, s83
	s_addc_u32 vcc_hi, vcc_hi, 0
	s_add_i32 s82, s82, 1
	s_setprio 0
	s_barrier
	v_add_u32_e32 v136, 0x1c000, v147
	ds_read_b128 v[166:169], v136
	ds_read_b128 v[170:173], v136 offset:1024
	ds_read_b128 v[174:177], v136 offset:2048
	ds_read_b128 v[178:181], v136 offset:3072
	ds_read_b128 v[202:205], v165 offset:32768
	ds_read_b128 v[208:211], v165 offset:33792
	ds_read_b128 v[212:215], v165 offset:34816
	ds_read_b128 v[216:219], v165 offset:35840
	ds_read_b128 v[220:223], v165 offset:36864
	ds_read_b128 v[224:227], v165 offset:37888
	ds_read_b128 v[228:231], v165 offset:38912
	ds_read_b128 v[232:235], v165 offset:39936
	v_lshl_add_u64 v[136:137], s[76:77], 0, v[0:1]
	s_add_i32 m0, s94, 0x0
	v_lshl_add_u64 v[144:145], s[76:77], 0, v[130:131]
	global_load_lds_dwordx4 v[136:137], off
	s_add_i32 m0, s94, 0x2000
	s_nop 0
	global_load_lds_dwordx4 v[144:145], off
	s_waitcnt vmcnt(6)
	s_waitcnt lgkmcnt(0)
	s_barrier
	s_setprio 1
	v_mfma_f32_16x16x32_bf16 v[118:121], v[166:169], v[202:205], v[118:121]
	v_mfma_f32_16x16x32_bf16 v[114:117], v[174:177], v[202:205], v[114:117]
	v_mfma_f32_16x16x32_bf16 v[102:105], v[166:169], v[212:215], v[102:105]
	v_lshl_add_u64 v[182:183], vcc, 0, v[0:1]
	s_add_i32 m0, s93, 0x14000
	v_lshl_add_u64 v[236:237], vcc, 0, v[130:131]
	global_load_lds_dwordx4 v[182:183], off
	v_mfma_f32_16x16x32_bf16 v[98:101], v[174:177], v[212:215], v[98:101]
	v_mfma_f32_16x16x32_bf16 v[86:89], v[166:169], v[220:223], v[86:89]
	v_mfma_f32_16x16x32_bf16 v[82:85], v[174:177], v[220:223], v[82:85]
	v_mfma_f32_16x16x32_bf16 v[70:73], v[166:169], v[228:231], v[70:73]
	v_mfma_f32_16x16x32_bf16 v[66:69], v[174:177], v[228:231], v[66:69]
	v_mfma_f32_16x16x32_bf16 v[118:121], v[170:173], v[208:211], v[118:121]
	s_add_i32 m0, s93, 0x16000
	s_nop 0
	global_load_lds_dwordx4 v[236:237], off
	v_mfma_f32_16x16x32_bf16 v[114:117], v[178:181], v[208:211], v[114:117]
	v_mfma_f32_16x16x32_bf16 v[102:105], v[170:173], v[216:219], v[102:105]
	v_mfma_f32_16x16x32_bf16 v[98:101], v[178:181], v[216:219], v[98:101]
	v_mfma_f32_16x16x32_bf16 v[86:89], v[170:173], v[224:227], v[86:89]
	v_mfma_f32_16x16x32_bf16 v[82:85], v[178:181], v[224:227], v[82:85]
	v_mfma_f32_16x16x32_bf16 v[70:73], v[170:173], v[232:235], v[70:73]
	v_mfma_f32_16x16x32_bf16 v[66:69], v[178:181], v[232:235], v[66:69]
	s_cmp_lt_u32 s82, s59
	s_cselect_b32 s83, 0x80, 0
	s_add_u32 s76, s76, s83
	s_addc_u32 s77, s77, 0
	s_add_u32 vcc_lo, vcc_lo, s83
	s_addc_u32 vcc_hi, vcc_hi, 0
	s_add_i32 s82, s82, 1
	s_setprio 0
	s_barrier
; #define PG8_STAGE(bufoff, gbase, voff) do { _Pragma("unroll") for (int _i = 0; _i < 2; ++_i) \
;         __builtin_amdgcn_global_load_lds((const unsigned*)((const char*)(gbase) + (voff)[_i]), (PG8_LAS unsigned*)(lds + (bufoff) + ldsw + _i * 8192), 16, 0, 0); } while (0)
; #define PG8_LDA(dst, b, h) do { _Pragma("unroll") for (int m = 0; m < 4; ++m) _Pragma("unroll") for (int k = 0; k < 2; ++k) dst[m][k] = *(const PG8_LAS bf16x8*)(lds + PG8_SA(b, h) + aoff + m * 2048 + k * 1024); } while (0)
; #define PG8_LDB(dst, b, h) do { _Pragma("unroll") for (int n = 0; n < 2; ++n) _Pragma("unroll") for (int k = 0; k < 2; ++k) dst[n][k] = *(const PG8_LAS bf16x8*)(lds + PG8_SB(b, h) + boff + n * 2048 + k * 1024); } while (0)
; #define PG8_MMA(ai, bj, At, Bt) do { __builtin_amdgcn_s_setprio(1); _Pragma("unroll") for (int m = 0; m < 4; ++m) _Pragma("unroll") for (int n = 0; n < 2; ++n) _Pragma("unroll") for (int k = 0; k < 2; ++k) \
;         acc[ai][bj][m][n] = __builtin_amdgcn_mfma_f32_16x16x32_bf16(Bt[n][k], At[m][k], acc[ai][bj][m][n], 0, 0, 0); __builtin_amdgcn_s_setprio(0); } while (0)
; #define PG8_WAIT_V(n) asm volatile("s_waitcnt vmcnt(" #n ")" ::: "memory")
; template <class Epi, class Sched, bool ALIGN_EPI = false, bool SP2 = false>
; __device__ __forceinline__ void gemm_phase(PG8_LAS unsigned char* lds, const Gemm g, const Sched& S, const Epi& E) {
;     ...
;             PG8_LDB(B0, 0, 0); PG8_LDB(B1, 0, 1); PG8_SCHED; PG8_LDA(At, 0, 0); PG8_STAGE(PG8_SA(1, 1), a1 + hstep, voffA);
;             PG8_WAIT_V(8); PG8_WAIT_L(0); PG8_BAR; PG8_MMA(0, 0, At, B0); PG8_MMA(0, 1, At, B1); PG8_BAR; PG8_SCHED;
;             PG8_LDA(At, 0, 1); PG8_STAGE(PG8_SB(0, 0), b2, voffB); PG8_STAGE(PG8_SB(0, 1), b2 + hstep, voffB); PG8_STAGE(PG8_SA(0, 0), a2, voffA);
;             PG8_WAIT_V(8); PG8_WAIT_L(0); PG8_BAR; PG8_MMA(1, 0, At, B0); PG8_MMA(1, 1, At, B1); PG8_BAR; PG8_SCHED;
;             PG8_LDB(B0, 1, 0); PG8_LDB(B1, 1, 1); PG8_SCHED; PG8_LDA(At, 1, 0); PG8_STAGE(PG8_SA(0, 1), a2 + hstep, voffA);
;             PG8_WAIT_V(8); PG8_WAIT_L(0); PG8_BAR; PG8_MMA(0, 0, At, B0); PG8_MMA(0, 1, At, B1); PG8_BAR; PG8_SCHED;
;             PG8_LDA(At, 1, 1); PG8_STAGE(PG8_SB(1, 0), b3, voffB); PG8_STAGE(PG8_SB(1, 1), b3 + hstep, voffB); PG8_STAGE(PG8_SA(1, 0), a3, voffA);
;             PG8_WAIT_V(8); PG8_WAIT_L(0); PG8_BAR; PG8_MMA(1, 0, At, B0); PG8_MMA(1, 1, At, B1); PG8_BAR; PG8_SCHED;
	v_add_u32_e32 v136, 0x10000, v147
	ds_read_b128 v[166:169], v136
	ds_read_b128 v[170:173], v136 offset:1024
	ds_read_b128 v[174:177], v136 offset:2048
	ds_read_b128 v[178:181], v136 offset:3072
	ds_read_b128 v[202:205], v165 offset:16384
	ds_read_b128 v[208:211], v165 offset:17408
	ds_read_b128 v[212:215], v165 offset:18432
	ds_read_b128 v[216:219], v165 offset:19456
	ds_read_b128 v[220:223], v165 offset:20480
	ds_read_b128 v[224:227], v165 offset:21504
	ds_read_b128 v[228:231], v165 offset:22528
	ds_read_b128 v[232:235], v165 offset:23552
	v_lshl_add_u64 v[136:137], s[76:77], 0, v[0:1]
	s_add_i32 m0, s94, 0x8000
	v_lshl_add_u64 v[144:145], s[76:77], 0, v[130:131]
	global_load_lds_dwordx4 v[136:137], off
	s_add_i32 m0, s94, 0xa000
	s_nop 0
	global_load_lds_dwordx4 v[144:145], off
	s_waitcnt vmcnt(6)
	s_waitcnt lgkmcnt(0)
	s_barrier
	s_setprio 1
	v_mfma_f32_16x16x32_bf16 v[118:121], v[166:169], v[202:205], v[118:121]
	v_mfma_f32_16x16x32_bf16 v[114:117], v[174:177], v[202:205], v[114:117]
	v_mfma_f32_16x16x32_bf16 v[102:105], v[166:169], v[212:215], v[102:105]
	v_lshl_add_u64 v[182:183], vcc, 0, v[0:1]
	s_add_i32 m0, s93, 0x1c000
	v_lshl_add_u64 v[236:237], vcc, 0, v[130:131]
	global_load_lds_dwordx4 v[182:183], off
	v_mfma_f32_16x16x32_bf16 v[98:101], v[174:177], v[212:215], v[98:101]
	v_mfma_f32_16x16x32_bf16 v[86:89], v[166:169], v[220:223], v[86:89]
	v_mfma_f32_16x16x32_bf16 v[82:85], v[174:177], v[220:223], v[82:85]
	v_mfma_f32_16x16x32_bf16 v[70:73], v[166:169], v[228:231], v[70:73]
	v_mfma_f32_16x16x32_bf16 v[66:69], v[174:177], v[228:231], v[66:69]
	v_mfma_f32_16x16x32_bf16 v[118:121], v[170:173], v[208:211], v[118:121]
	s_add_i32 m0, s93, 0x1e000
	s_nop 0
	global_load_lds_dwordx4 v[236:237], off
	v_mfma_f32_16x16x32_bf16 v[114:117], v[178:181], v[208:211], v[114:117]
	v_mfma_f32_16x16x32_bf16 v[102:105], v[170:173], v[216:219], v[102:105]
	v_mfma_f32_16x16x32_bf16 v[98:101], v[178:181], v[216:219], v[98:101]
	v_mfma_f32_16x16x32_bf16 v[86:89], v[170:173], v[224:227], v[86:89]
	v_mfma_f32_16x16x32_bf16 v[82:85], v[178:181], v[224:227], v[82:85]
	v_mfma_f32_16x16x32_bf16 v[70:73], v[170:173], v[232:235], v[70:73]
	v_mfma_f32_16x16x32_bf16 v[66:69], v[178:181], v[232:235], v[66:69]
	s_cmp_lt_u32 s82, s59
	s_cselect_b32 s83, 0x80, 0
	s_add_u32 s76, s76, s83
	s_addc_u32 s77, s77, 0
	s_add_u32 vcc_lo, vcc_lo, s83
	s_addc_u32 vcc_hi, vcc_hi, 0
	s_add_i32 s82, s82, 1
	s_setprio 0
	s_barrier
	v_add_u32_e32 v136, 0x18000, v147
	ds_read_b128 v[166:169], v136
	ds_read_b128 v[170:173], v136 offset:1024
	ds_read_b128 v[174:177], v136 offset:2048
	ds_read_b128 v[178:181], v136 offset:3072
	ds_read_b128 v[202:205], v165 offset:49152
	ds_read_b128 v[208:211], v165 offset:50176
	ds_read_b128 v[212:215], v165 offset:51200
	ds_read_b128 v[216:219], v165 offset:52224
	ds_read_b128 v[220:223], v165 offset:53248
	ds_read_b128 v[224:227], v165 offset:54272
	ds_read_b128 v[228:231], v165 offset:55296
	ds_read_b128 v[232:235], v165 offset:56320
	v_lshl_add_u64 v[136:137], s[76:77], 0, v[0:1]
	s_add_i32 m0, s94, 0x4000
	v_lshl_add_u64 v[144:145], s[76:77], 0, v[130:131]
	global_load_lds_dwordx4 v[136:137], off
	s_add_i32 m0, s94, 0x6000
	s_nop 0
	global_load_lds_dwordx4 v[144:145], off
	s_waitcnt vmcnt(6)
	s_waitcnt lgkmcnt(0)
	s_barrier
	s_setprio 1
	v_mfma_f32_16x16x32_bf16 v[118:121], v[166:169], v[202:205], v[118:121]
	v_mfma_f32_16x16x32_bf16 v[114:117], v[174:177], v[202:205], v[114:117]
	v_mfma_f32_16x16x32_bf16 v[102:105], v[166:169], v[212:215], v[102:105]
	v_lshl_add_u64 v[182:183], vcc, 0, v[0:1]
	s_add_i32 m0, s93, 0x10000
	v_lshl_add_u64 v[236:237], vcc, 0, v[130:131]
	global_load_lds_dwordx4 v[182:183], off
	v_mfma_f32_16x16x32_bf16 v[98:101], v[174:177], v[212:215], v[98:101]
	v_mfma_f32_16x16x32_bf16 v[86:89], v[166:169], v[220:223], v[86:89]
	v_mfma_f32_16x16x32_bf16 v[82:85], v[174:177], v[220:223], v[82:85]
	v_mfma_f32_16x16x32_bf16 v[70:73], v[166:169], v[228:231], v[70:73]
	v_mfma_f32_16x16x32_bf16 v[66:69], v[174:177], v[228:231], v[66:69]
	v_mfma_f32_16x16x32_bf16 v[118:121], v[170:173], v[208:211], v[118:121]
	s_add_i32 m0, s93, 0x12000
	s_nop 0
	global_load_lds_dwordx4 v[236:237], off
	v_mfma_f32_16x16x32_bf16 v[114:117], v[178:181], v[208:211], v[114:117]
	v_mfma_f32_16x16x32_bf16 v[102:105], v[170:173], v[216:219], v[102:105]
	v_mfma_f32_16x16x32_bf16 v[98:101], v[178:181], v[216:219], v[98:101]
	v_mfma_f32_16x16x32_bf16 v[86:89], v[170:173], v[224:227], v[86:89]
	v_mfma_f32_16x16x32_bf16 v[82:85], v[178:181], v[224:227], v[82:85]
	v_mfma_f32_16x16x32_bf16 v[70:73], v[170:173], v[232:235], v[70:73]
	v_mfma_f32_16x16x32_bf16 v[66:69], v[178:181], v[232:235], v[66:69]
	s_cmp_lt_u32 s82, s59
	s_cselect_b32 s83, 0x80, 0
	s_add_u32 s76, s76, s83
	s_addc_u32 s77, s77, 0
	s_add_u32 vcc_lo, vcc_lo, s83
	s_addc_u32 vcc_hi, vcc_hi, 0
	s_add_i32 s82, s82, 1
	s_setprio 0
	s_barrier
	s_add_i32 s83, s82, -3
	s_cmp_lt_u32 s83, s79
	s_cbranch_scc1 .Lkq_3_loop

; template <class Epi, class Sched, bool ALIGN_EPI = false, bool SP2 = false>
; __device__ __forceinline__ void gemm_phase(PG8_LAS unsigned char* lds, const Gemm g, const Sched& S, const Epi& E) {
;     ...
;         PG8_STAGE(PG8_SB(0, 0), cB, voffB); PG8_STAGE(PG8_SB(0, 1), cB + hstep, voffB); PG8_STAGE(PG8_SA(0, 0), cA, voffA); PG8_STAGE(PG8_SA(0, 1), cA + hstep, voffA);
;         if (wr == 1) PG8_BAR;
;         PG8_WAIT_V(2); PG8_BAR;
;         PG8_STAGE(PG8_SB(1, 0), cB + kstep, voffB); PG8_STAGE(PG8_SA(1, 0), cA + kstep, voffA); PG8_STAGE(PG8_SB(1, 1), cB + hstep + kstep, voffB);
;         PG8_WAIT_V(6); PG8_BAR;
;     } else {
;         PG8_STAGE(PG8_SB(0, 0), cB, voffB); PG8_STAGE(PG8_SA(0, 0), cA, voffA); PG8_STAGE(PG8_SB(0, 1), cB + hstep, voffB); PG8_STAGE(PG8_SA(0, 1), cA + hstep, voffA);
;         if (wr == 1) PG8_BAR;
;         PG8_WAIT_V(4); PG8_BAR;
;         PG8_STAGE(PG8_SB(1, 0), cB + kstep, voffB); PG8_STAGE(PG8_SA(1, 0), cA + kstep, voffA); PG8_STAGE(PG8_SB(1, 1), cB + hstep + kstep, voffB);
;         PG8_WAIT_V(6); PG8_BAR;
;     }
;     for (;;) {
;         const bool has_next = S.next(ui + 1, nxt);
;         const char* nA = has_next ? (const char*)g.A + (size_t)nxt.pm * tstep : cA; const char* nB = has_next ? (const char*)g.Bt + (size_t)nxt.pn * tstep : cB;
;         for (int t = 0; t < nt; t += 2) {
;             const bool last = (t == nt - 2);
;             const char* a1 = cA + (size_t)(t + 1) * kstep;
;             const char* a2 = last ? nA : cA + (size_t)(t + 2) * kstep; const char* b2 = last ? nB : cB + (size_t)(t + 2) * kstep;
;             const char* a3 = a2 + kstep; const char* b3 = b2 + kstep;
;             if (last && has_next) S.a_ready(nxt);
;             if constexpr (SP2) {
;             PG8_LDB(B0, 0, 0); PG8_LDB(B1, 0, 1); PG8_SCHED; PG8_LDA(At, 0, 0); PG8_STAGE(PG8_SA(1, 1), a1 + hstep, voffA);
;             PG8_WAIT_V(8); PG8_WAIT_L(0); PG8_BAR; PG8_MMA(0, 0, At, B0); PG8_MMA(0, 1, At, B1); PG8_BAR; PG8_SCHED;
;             PG8_LDA(At, 0, 1); PG8_STAGE(PG8_SB(0, 0), b2, voffB); PG8_STAGE(PG8_SB(0, 1), b2 + hstep, voffB); PG8_STAGE(PG8_SA(0, 0), a2, voffA);
;             PG8_WAIT_V(8); PG8_WAIT_L(0); PG8_BAR; PG8_MMA(1, 0, At, B0); PG8_MMA(1, 1, At, B1); PG8_BAR; PG8_SCHED;
;             PG8_LDB(B0, 1, 0); PG8_LDB(B1, 1, 1); PG8_SCHED; PG8_LDA(At, 1, 0); PG8_STAGE(PG8_SA(0, 1), a2 + hstep, voffA);
.Lkq_4:
	s_waitcnt vmcnt(0)
	s_barrier
	s_mov_b64 s[76:77], s[48:49]
	s_add_u32 vcc_lo, s80, 0xffffff80
	s_addc_u32 vcc_hi, s81, -1
	s_add_u32 s76, s76, s10
	s_addc_u32 s77, s77, 0
	s_add_u32 vcc_lo, vcc_lo, s10
	s_addc_u32 vcc_hi, vcc_hi, 0
	v_lshl_add_u64 v[136:137], s[76:77], 0, v[0:1]
	s_add_i32 m0, s94, 0xc000
	v_lshl_add_u64 v[144:145], s[76:77], 0, v[130:131]
	global_load_lds_dwordx4 v[136:137], off
	s_add_i32 m0, s94, 0xe000
	s_nop 0
	global_load_lds_dwordx4 v[144:145], off
	s_add_u32 s76, s76, 0x80
	s_addc_u32 s77, s77, 0
	s_add_u32 vcc_lo, vcc_lo, 0x80
	s_addc_u32 vcc_hi, vcc_hi, 0
	v_lshl_add_u64 v[136:137], s[76:77], 0, v[0:1]
	s_add_i32 m0, s94, 0x0
	v_lshl_add_u64 v[144:145], s[76:77], 0, v[130:131]
	global_load_lds_dwordx4 v[136:137], off
	s_add_i32 m0, s94, 0x2000
	s_nop 0
	global_load_lds_dwordx4 v[144:145], off
	v_lshl_add_u64 v[182:183], vcc, 0, v[0:1]
	s_add_i32 m0, s93, 0x10000
	v_lshl_add_u64 v[236:237], vcc, 0, v[130:131]
	global_load_lds_dwordx4 v[182:183], off
	s_add_i32 m0, s93, 0x12000
	s_nop 0
	global_load_lds_dwordx4 v[236:237], off
	s_add_u32 s76, s76, 0x80
	s_addc_u32 s77, s77, 0
	s_add_u32 vcc_lo, vcc_lo, 0x80
	s_addc_u32 vcc_hi, vcc_hi, 0
	s_mov_b32 s82, 3
	s_add_i32 s59, s79, -1
	v_add_u32_e32 v136, 0x14000, v147
	ds_read_b128 v[166:169], v136
	ds_read_b128 v[170:173], v136 offset:1024
	ds_read_b128 v[174:177], v136 offset:2048
	ds_read_b128 v[178:181], v136 offset:3072
	ds_read_b128 v[202:205], v165 offset:16384
	ds_read_b128 v[208:211], v165 offset:17408
	ds_read_b128 v[212:215], v165 offset:18432
	ds_read_b128 v[216:219], v165 offset:19456
	ds_read_b128 v[220:223], v165 offset:20480
	ds_read_b128 v[224:227], v165 offset:21504
	ds_read_b128 v[228:231], v165 offset:22528
	ds_read_b128 v[232:235], v165 offset:23552
	v_lshl_add_u64 v[136:137], s[76:77], 0, v[0:1]
	s_add_i32 m0, s94, 0x8000
	v_lshl_add_u64 v[144:145], s[76:77], 0, v[130:131]
	global_load_lds_dwordx4 v[136:137], off
	s_add_i32 m0, s94, 0xa000
	s_nop 0
	global_load_lds_dwordx4 v[144:145], off
	s_waitcnt vmcnt(6)
	s_waitcnt lgkmcnt(0)
	s_barrier
	s_setprio 1
	v_mfma_f32_16x16x32_bf16 v[54:57], v[166:169], v[202:205], 0
	v_mfma_f32_16x16x32_bf16 v[50:53], v[174:177], v[202:205], 0
	v_mfma_f32_16x16x32_bf16 v[38:41], v[166:169], v[212:215], 0
	v_lshl_add_u64 v[182:183], vcc, 0, v[0:1]
	s_add_i32 m0, s93, 0x18000
	v_lshl_add_u64 v[236:237], vcc, 0, v[130:131]
	global_load_lds_dwordx4 v[182:183], off
	v_mfma_f32_16x16x32_bf16 v[34:37], v[174:177], v[212:215], 0
	v_mfma_f32_16x16x32_bf16 v[22:25], v[166:169], v[220:223], 0
	v_mfma_f32_16x16x32_bf16 v[18:21], v[174:177], v[220:223], 0
	v_mfma_f32_16x16x32_bf16 v[6:9], v[166:169], v[228:231], 0
	v_mfma_f32_16x16x32_bf16 v[2:5], v[174:177], v[228:231], 0
	v_mfma_f32_16x16x32_bf16 v[54:57], v[170:173], v[208:211], v[54:57]
	s_add_i32 m0, s93, 0x1a000
	s_nop 0
	global_load_lds_dwordx4 v[236:237], off
	v_mfma_f32_16x16x32_bf16 v[50:53], v[178:181], v[208:211], v[50:53]
	v_mfma_f32_16x16x32_bf16 v[38:41], v[170:173], v[216:219], v[38:41]
	v_mfma_f32_16x16x32_bf16 v[34:37], v[178:181], v[216:219], v[34:37]
	v_mfma_f32_16x16x32_bf16 v[22:25], v[170:173], v[224:227], v[22:25]
	v_mfma_f32_16x16x32_bf16 v[18:21], v[178:181], v[224:227], v[18:21]
	v_mfma_f32_16x16x32_bf16 v[6:9], v[170:173], v[232:235], v[6:9]
	v_mfma_f32_16x16x32_bf16 v[2:5], v[178:181], v[232:235], v[2:5]
	s_cmp_lt_u32 s82, s59
	s_cselect_b32 s83, 0x80, 0
	s_add_u32 s76, s76, s83
	s_addc_u32 s77, s77, 0
	s_add_u32 vcc_lo, vcc_lo, s83
	s_addc_u32 vcc_hi, vcc_hi, 0
	s_add_i32 s82, s82, 1
	s_setprio 0
	s_barrier
	v_add_u32_e32 v136, 0x1c000, v147
	ds_read_b128 v[166:169], v136
	ds_read_b128 v[170:173], v136 offset:1024
	ds_read_b128 v[174:177], v136 offset:2048
	ds_read_b128 v[178:181], v136 offset:3072
	ds_read_b128 v[202:205], v165 offset:49152
	ds_read_b128 v[208:211], v165 offset:50176
	ds_read_b128 v[212:215], v165 offset:51200
	ds_read_b128 v[216:219], v165 offset:52224
	ds_read_b128 v[220:223], v165 offset:53248
	ds_read_b128 v[224:227], v165 offset:54272
	ds_read_b128 v[228:231], v165 offset:55296
	ds_read_b128 v[232:235], v165 offset:56320
	v_lshl_add_u64 v[136:137], s[76:77], 0, v[0:1]
	s_add_i32 m0, s94, 0x4000
	v_lshl_add_u64 v[144:145], s[76:77], 0, v[130:131]
	global_load_lds_dwordx4 v[136:137], off
	s_add_i32 m0, s94, 0x6000
	s_nop 0
	global_load_lds_dwordx4 v[144:145], off
	s_waitcnt vmcnt(6)
	s_waitcnt lgkmcnt(0)
	s_barrier
	s_setprio 1
	v_mfma_f32_16x16x32_bf16 v[54:57], v[166:169], v[202:205], v[54:57]
	v_mfma_f32_16x16x32_bf16 v[50:53], v[174:177], v[202:205], v[50:53]
	v_mfma_f32_16x16x32_bf16 v[38:41], v[166:169], v[212:215], v[38:41]
	v_lshl_add_u64 v[182:183], vcc, 0, v[0:1]
	s_add_i32 m0, s93, 0x14000
	v_lshl_add_u64 v[236:237], vcc, 0, v[130:131]
	global_load_lds_dwordx4 v[182:183], off
	v_mfma_f32_16x16x32_bf16 v[34:37], v[174:177], v[212:215], v[34:37]
	v_mfma_f32_16x16x32_bf16 v[22:25], v[166:169], v[220:223], v[22:25]
	v_mfma_f32_16x16x32_bf16 v[18:21], v[174:177], v[220:223], v[18:21]
	v_mfma_f32_16x16x32_bf16 v[6:9], v[166:169], v[228:231], v[6:9]
	v_mfma_f32_16x16x32_bf16 v[2:5], v[174:177], v[228:231], v[2:5]
	v_mfma_f32_16x16x32_bf16 v[54:57], v[170:173], v[208:211], v[54:57]
	s_add_i32 m0, s93, 0x16000
	s_nop 0
	global_load_lds_dwordx4 v[236:237], off
	v_mfma_f32_16x16x32_bf16 v[50:53], v[178:181], v[208:211], v[50:53]
	v_mfma_f32_16x16x32_bf16 v[38:41], v[170:173], v[216:219], v[38:41]
	v_mfma_f32_16x16x32_bf16 v[34:37], v[178:181], v[216:219], v[34:37]
	v_mfma_f32_16x16x32_bf16 v[22:25], v[170:173], v[224:227], v[22:25]
	v_mfma_f32_16x16x32_bf16 v[18:21], v[178:181], v[224:227], v[18:21]
	v_mfma_f32_16x16x32_bf16 v[6:9], v[170:173], v[232:235], v[6:9]
	v_mfma_f32_16x16x32_bf16 v[2:5], v[178:181], v[232:235], v[2:5]
	s_cmp_lt_u32 s82, s59
	s_cselect_b32 s83, 0x80, 0
	s_add_u32 s76, s76, s83
	s_addc_u32 s77, s77, 0
	s_add_u32 vcc_lo, vcc_lo, s83
	s_addc_u32 vcc_hi, vcc_hi, 0
	s_add_i32 s82, s82, 1
	s_setprio 0
	s_barrier
; #define PG8_STAGE(bufoff, gbase, voff) do { _Pragma("unroll") for (int _i = 0; _i < 2; ++_i) \
;         __builtin_amdgcn_global_load_lds((const unsigned*)((const char*)(gbase) + (voff)[_i]), (PG8_LAS unsigned*)(lds + (bufoff) + ldsw + _i * 8192), 16, 0, 0); } while (0)
; #define PG8_LDA(dst, b, h) do { _Pragma("unroll") for (int m = 0; m < 4; ++m) _Pragma("unroll") for (int k = 0; k < 2; ++k) dst[m][k] = *(const PG8_LAS bf16x8*)(lds + PG8_SA(b, h) + aoff + m * 2048 + k * 1024); } while (0)
; #define PG8_LDB(dst, b, h) do { _Pragma("unroll") for (int n = 0; n < 2; ++n) _Pragma("unroll") for (int k = 0; k < 2; ++k) dst[n][k] = *(const PG8_LAS bf16x8*)(lds + PG8_SB(b, h) + boff + n * 2048 + k * 1024); } while (0)
; #define PG8_MMA(ai, bj, At, Bt) do { __builtin_amdgcn_s_setprio(1); _Pragma("unroll") for (int m = 0; m < 4; ++m) _Pragma("unroll") for (int n = 0; n < 2; ++n) _Pragma("unroll") for (int k = 0; k < 2; ++k) \
;         acc[ai][bj][m][n] = __builtin_amdgcn_mfma_f32_16x16x32_bf16(Bt[n][k], At[m][k], acc[ai][bj][m][n], 0, 0, 0); __builtin_amdgcn_s_setprio(0); } while (0)
; #define PG8_WAIT_V(n) asm volatile("s_waitcnt vmcnt(" #n ")" ::: "memory")
; template <class Epi, class Sched, bool ALIGN_EPI = false, bool SP2 = false>
; __device__ __forceinline__ void gemm_phase(PG8_LAS unsigned char* lds, const Gemm g, const Sched& S, const Epi& E) {
;     ...
;             PG8_LDB(B0, 0, 0); PG8_LDB(B1, 0, 1); PG8_SCHED; PG8_LDA(At, 0, 0); PG8_STAGE(PG8_SA(1, 1), a1 + hstep, voffA);
;             PG8_WAIT_V(8); PG8_WAIT_L(0); PG8_BAR; PG8_MMA(0, 0, At, B0); PG8_MMA(0, 1, At, B1); PG8_BAR; PG8_SCHED;
;             PG8_LDA(At, 0, 1); PG8_STAGE(PG8_SB(0, 0), b2, voffB); PG8_STAGE(PG8_SB(0, 1), b2 + hstep, voffB); PG8_STAGE(PG8_SA(0, 0), a2, voffA);
;             PG8_WAIT_V(8); PG8_WAIT_L(0); PG8_BAR; PG8_MMA(1, 0, At, B0); PG8_MMA(1, 1, At, B1); PG8_BAR; PG8_SCHED;
;             PG8_LDB(B0, 1, 0); PG8_LDB(B1, 1, 1); PG8_SCHED; PG8_LDA(At, 1, 0); PG8_STAGE(PG8_SA(0, 1), a2 + hstep, voffA);
;             PG8_WAIT_V(8); PG8_WAIT_L(0); PG8_BAR; PG8_MMA(0, 0, At, B0); PG8_MMA(0, 1, At, B1); PG8_BAR; PG8_SCHED;
;             PG8_LDA(At, 1, 1); PG8_STAGE(PG8_SB(1, 0), b3, voffB); PG8_STAGE(PG8_SB(1, 1), b3 + hstep, voffB); PG8_STAGE(PG8_SA(1, 0), a3, voffA);
;             PG8_WAIT_V(8); PG8_WAIT_L(0); PG8_BAR; PG8_MMA(1, 0, At, B0); PG8_MMA(1, 1, At, B1); PG8_BAR; PG8_SCHED;
	v_add_u32_e32 v136, 0x10000, v147
	ds_read_b128 v[166:169], v136
	ds_read_b128 v[170:173], v136 offset:1024
	ds_read_b128 v[174:177], v136 offset:2048
	ds_read_b128 v[178:181], v136 offset:3072
	ds_read_b128 v[202:205], v165
	ds_read_b128 v[208:211], v165 offset:1024
	ds_read_b128 v[212:215], v165 offset:2048
	ds_read_b128 v[216:219], v165 offset:3072
	ds_read_b128 v[220:223], v165 offset:4096
	ds_read_b128 v[224:227], v165 offset:5120
	ds_read_b128 v[228:231], v165 offset:6144
	ds_read_b128 v[232:235], v165 offset:7168
	v_lshl_add_u64 v[136:137], s[76:77], 0, v[0:1]
	s_add_i32 m0, s94, 0xc000
	v_lshl_add_u64 v[144:145], s[76:77], 0, v[130:131]
	global_load_lds_dwordx4 v[136:137], off
	s_add_i32 m0, s94, 0xe000
	s_nop 0
	global_load_lds_dwordx4 v[144:145], off
	s_waitcnt vmcnt(6)
	s_waitcnt lgkmcnt(0)
	s_barrier
	s_setprio 1
	v_mfma_f32_16x16x32_bf16 v[54:57], v[166:169], v[202:205], v[54:57]
	v_mfma_f32_16x16x32_bf16 v[50:53], v[174:177], v[202:205], v[50:53]
	v_mfma_f32_16x16x32_bf16 v[38:41], v[166:169], v[212:215], v[38:41]
	v_lshl_add_u64 v[182:183], vcc, 0, v[0:1]
	s_add_i32 m0, s93, 0x1c000
	v_lshl_add_u64 v[236:237], vcc, 0, v[130:131]
	global_load_lds_dwordx4 v[182:183], off
	v_mfma_f32_16x16x32_bf16 v[34:37], v[174:177], v[212:215], v[34:37]
	v_mfma_f32_16x16x32_bf16 v[22:25], v[166:169], v[220:223], v[22:25]
	v_mfma_f32_16x16x32_bf16 v[18:21], v[174:177], v[220:223], v[18:21]
	v_mfma_f32_16x16x32_bf16 v[6:9], v[166:169], v[228:231], v[6:9]
	v_mfma_f32_16x16x32_bf16 v[2:5], v[174:177], v[228:231], v[2:5]
	v_mfma_f32_16x16x32_bf16 v[54:57], v[170:173], v[208:211], v[54:57]
	s_add_i32 m0, s93, 0x1e000
	s_nop 0
	global_load_lds_dwordx4 v[236:237], off
	v_mfma_f32_16x16x32_bf16 v[50:53], v[178:181], v[208:211], v[50:53]
	v_mfma_f32_16x16x32_bf16 v[38:41], v[170:173], v[216:219], v[38:41]
	v_mfma_f32_16x16x32_bf16 v[34:37], v[178:181], v[216:219], v[34:37]
	v_mfma_f32_16x16x32_bf16 v[22:25], v[170:173], v[224:227], v[22:25]
	v_mfma_f32_16x16x32_bf16 v[18:21], v[178:181], v[224:227], v[18:21]
	v_mfma_f32_16x16x32_bf16 v[6:9], v[170:173], v[232:235], v[6:9]
	v_mfma_f32_16x16x32_bf16 v[2:5], v[178:181], v[232:235], v[2:5]
	s_cmp_lt_u32 s82, s59
	s_cselect_b32 s83, 0x80, 0
	s_add_u32 s76, s76, s83
	s_addc_u32 s77, s77, 0
	s_add_u32 vcc_lo, vcc_lo, s83
	s_addc_u32 vcc_hi, vcc_hi, 0
	s_add_i32 s82, s82, 1
	s_setprio 0
	s_barrier
	v_add_u32_e32 v136, 0x18000, v147
	ds_read_b128 v[166:169], v136
	ds_read_b128 v[170:173], v136 offset:1024
	ds_read_b128 v[174:177], v136 offset:2048
	ds_read_b128 v[178:181], v136 offset:3072
	ds_read_b128 v[202:205], v165 offset:32768
	ds_read_b128 v[208:211], v165 offset:33792
	ds_read_b128 v[212:215], v165 offset:34816
	ds_read_b128 v[216:219], v165 offset:35840
	ds_read_b128 v[220:223], v165 offset:36864
	ds_read_b128 v[224:227], v165 offset:37888
	ds_read_b128 v[228:231], v165 offset:38912
	ds_read_b128 v[232:235], v165 offset:39936
	v_lshl_add_u64 v[136:137], s[76:77], 0, v[0:1]
	s_add_i32 m0, s94, 0x0
	v_lshl_add_u64 v[144:145], s[76:77], 0, v[130:131]
	global_load_lds_dwordx4 v[136:137], off
	s_add_i32 m0, s94, 0x2000
	s_nop 0
	global_load_lds_dwordx4 v[144:145], off
	s_waitcnt vmcnt(6)
	s_waitcnt lgkmcnt(0)
	s_barrier
	s_setprio 1
	v_mfma_f32_16x16x32_bf16 v[54:57], v[166:169], v[202:205], v[54:57]
	v_mfma_f32_16x16x32_bf16 v[50:53], v[174:177], v[202:205], v[50:53]
	v_mfma_f32_16x16x32_bf16 v[38:41], v[166:169], v[212:215], v[38:41]
	v_lshl_add_u64 v[182:183], vcc, 0, v[0:1]
	s_add_i32 m0, s93, 0x10000
	v_lshl_add_u64 v[236:237], vcc, 0, v[130:131]
	global_load_lds_dwordx4 v[182:183], off
	v_mfma_f32_16x16x32_bf16 v[34:37], v[174:177], v[212:215], v[34:37]
	v_mfma_f32_16x16x32_bf16 v[22:25], v[166:169], v[220:223], v[22:25]
	v_mfma_f32_16x16x32_bf16 v[18:21], v[174:177], v[220:223], v[18:21]
	v_mfma_f32_16x16x32_bf16 v[6:9], v[166:169], v[228:231], v[6:9]
	v_mfma_f32_16x16x32_bf16 v[2:5], v[174:177], v[228:231], v[2:5]
	v_mfma_f32_16x16x32_bf16 v[54:57], v[170:173], v[208:211], v[54:57]
	s_add_i32 m0, s93, 0x12000
	s_nop 0
	global_load_lds_dwordx4 v[236:237], off
	v_mfma_f32_16x16x32_bf16 v[50:53], v[178:181], v[208:211], v[50:53]
	v_mfma_f32_16x16x32_bf16 v[38:41], v[170:173], v[216:219], v[38:41]
	v_mfma_f32_16x16x32_bf16 v[34:37], v[178:181], v[216:219], v[34:37]
	v_mfma_f32_16x16x32_bf16 v[22:25], v[170:173], v[224:227], v[22:25]
	v_mfma_f32_16x16x32_bf16 v[18:21], v[178:181], v[224:227], v[18:21]
	v_mfma_f32_16x16x32_bf16 v[6:9], v[170:173], v[232:235], v[6:9]
	v_mfma_f32_16x16x32_bf16 v[2:5], v[178:181], v[232:235], v[2:5]
	s_cmp_lt_u32 s82, s59
	s_cselect_b32 s83, 0x80, 0
	s_add_u32 s76, s76, s83
	s_addc_u32 s77, s77, 0
	s_add_u32 vcc_lo, vcc_lo, s83
	s_addc_u32 vcc_hi, vcc_hi, 0
	s_add_i32 s82, s82, 1
	s_setprio 0
	s_barrier
	s_add_i32 s83, s82, -3
	s_cmp_lt_u32 s83, s79
	s_cbranch_scc0 .Lkq_4_post
; #define PG8_STAGE(bufoff, gbase, voff) do { _Pragma("unroll") for (int _i = 0; _i < 2; ++_i) \
;         __builtin_amdgcn_global_load_lds((const unsigned*)((const char*)(gbase) + (voff)[_i]), (PG8_LAS unsigned*)(lds + (bufoff) + ldsw + _i * 8192), 16, 0, 0); } while (0)
; #define PG8_LDA(dst, b, h) do { _Pragma("unroll") for (int m = 0; m < 4; ++m) _Pragma("unroll") for (int k = 0; k < 2; ++k) dst[m][k] = *(const PG8_LAS bf16x8*)(lds + PG8_SA(b, h) + aoff + m * 2048 + k * 1024); } while (0)
; #define PG8_LDB(dst, b, h) do { _Pragma("unroll") for (int n = 0; n < 2; ++n) _Pragma("unroll") for (int k = 0; k < 2; ++k) dst[n][k] = *(const PG8_LAS bf16x8*)(lds + PG8_SB(b, h) + boff + n * 2048 + k * 1024); } while (0)
; #define PG8_MMA(ai, bj, At, Bt) do { __builtin_amdgcn_s_setprio(1); _Pragma("unroll") for (int m = 0; m < 4; ++m) _Pragma("unroll") for (int n = 0; n < 2; ++n) _Pragma("unroll") for (int k = 0; k < 2; ++k) \
;         acc[ai][bj][m][n] = __builtin_amdgcn_mfma_f32_16x16x32_bf16(Bt[n][k], At[m][k], acc[ai][bj][m][n], 0, 0, 0); __builtin_amdgcn_s_setprio(0); } while (0)
; #define PG8_WAIT_V(n) asm volatile("s_waitcnt vmcnt(" #n ")" ::: "memory")
; template <class Epi, class Sched, bool ALIGN_EPI = false, bool SP2 = false>
; __device__ __forceinline__ void gemm_phase(PG8_LAS unsigned char* lds, const Gemm g, const Sched& S, const Epi& E) {
;     ...
;             PG8_LDB(B0, 0, 0); PG8_LDB(B1, 0, 1); PG8_SCHED; PG8_LDA(At, 0, 0); PG8_STAGE(PG8_SA(1, 1), a1 + hstep, voffA);
;             PG8_WAIT_V(8); PG8_WAIT_L(0); PG8_BAR; PG8_MMA(0, 0, At, B0); PG8_MMA(0, 1, At, B1); PG8_BAR; PG8_SCHED;
;             PG8_LDA(At, 0, 1); PG8_STAGE(PG8_SB(0, 0), b2, voffB); PG8_STAGE(PG8_SB(0, 1), b2 + hstep, voffB); PG8_STAGE(PG8_SA(0, 0), a2, voffA);
;             PG8_WAIT_V(8); PG8_WAIT_L(0); PG8_BAR; PG8_MMA(1, 0, At, B0); PG8_MMA(1, 1, At, B1); PG8_BAR; PG8_SCHED;
;             PG8_LDB(B0, 1, 0); PG8_LDB(B1, 1, 1); PG8_SCHED; PG8_LDA(At, 1, 0); PG8_STAGE(PG8_SA(0, 1), a2 + hstep, voffA);
;             PG8_WAIT_V(8); PG8_WAIT_L(0); PG8_BAR; PG8_MMA(0, 0, At, B0); PG8_MMA(0, 1, At, B1); PG8_BAR; PG8_SCHED;
;             PG8_LDA(At, 1, 1); PG8_STAGE(PG8_SB(1, 0), b3, voffB); PG8_STAGE(PG8_SB(1, 1), b3 + hstep, voffB); PG8_STAGE(PG8_SA(1, 0), a3, voffA);
;             PG8_WAIT_V(8); PG8_WAIT_L(0); PG8_BAR; PG8_MMA(1, 0, At, B0); PG8_MMA(1, 1, At, B1); PG8_BAR; PG8_SCHED;
.Lkq_4_loop:
	v_add_u32_e32 v136, 0x14000, v147
	ds_read_b128 v[166:169], v136
	ds_read_b128 v[170:173], v136 offset:1024
	ds_read_b128 v[174:177], v136 offset:2048
	ds_read_b128 v[178:181], v136 offset:3072
	ds_read_b128 v[202:205], v165 offset:16384
	ds_read_b128 v[208:211], v165 offset:17408
	ds_read_b128 v[212:215], v165 offset:18432
	ds_read_b128 v[216:219], v165 offset:19456
	ds_read_b128 v[220:223], v165 offset:20480
	ds_read_b128 v[224:227], v165 offset:21504
	ds_read_b128 v[228:231], v165 offset:22528
	ds_read_b128 v[232:235], v165 offset:23552
	v_lshl_add_u64 v[136:137], s[76:77], 0, v[0:1]
	s_add_i32 m0, s94, 0x8000
	v_lshl_add_u64 v[144:145], s[76:77], 0, v[130:131]
	global_load_lds_dwordx4 v[136:137], off
	s_add_i32 m0, s94, 0xa000
	s_nop 0
	global_load_lds_dwordx4 v[144:145], off
	s_waitcnt vmcnt(6)
	s_waitcnt lgkmcnt(0)
	s_barrier
	s_setprio 1
	v_mfma_f32_16x16x32_bf16 v[54:57], v[166:169], v[202:205], v[54:57]
	v_mfma_f32_16x16x32_bf16 v[50:53], v[174:177], v[202:205], v[50:53]
	v_mfma_f32_16x16x32_bf16 v[38:41], v[166:169], v[212:215], v[38:41]
	v_lshl_add_u64 v[182:183], vcc, 0, v[0:1]
	s_add_i32 m0, s93, 0x18000
	v_lshl_add_u64 v[236:237], vcc, 0, v[130:131]
	global_load_lds_dwordx4 v[182:183], off
	v_mfma_f32_16x16x32_bf16 v[34:37], v[174:177], v[212:215], v[34:37]
	v_mfma_f32_16x16x32_bf16 v[22:25], v[166:169], v[220:223], v[22:25]
	v_mfma_f32_16x16x32_bf16 v[18:21], v[174:177], v[220:223], v[18:21]
	v_mfma_f32_16x16x32_bf16 v[6:9], v[166:169], v[228:231], v[6:9]
	v_mfma_f32_16x16x32_bf16 v[2:5], v[174:177], v[228:231], v[2:5]
	v_mfma_f32_16x16x32_bf16 v[54:57], v[170:173], v[208:211], v[54:57]
	s_add_i32 m0, s93, 0x1a000
	s_nop 0
	global_load_lds_dwordx4 v[236:237], off
	v_mfma_f32_16x16x32_bf16 v[50:53], v[178:181], v[208:211], v[50:53]
	v_mfma_f32_16x16x32_bf16 v[38:41], v[170:173], v[216:219], v[38:41]
	v_mfma_f32_16x16x32_bf16 v[34:37], v[178:181], v[216:219], v[34:37]
	v_mfma_f32_16x16x32_bf16 v[22:25], v[170:173], v[224:227], v[22:25]
	v_mfma_f32_16x16x32_bf16 v[18:21], v[178:181], v[224:227], v[18:21]
	v_mfma_f32_16x16x32_bf16 v[6:9], v[170:173], v[232:235], v[6:9]
	v_mfma_f32_16x16x32_bf16 v[2:5], v[178:181], v[232:235], v[2:5]
	s_cmp_lt_u32 s82, s59
	s_cselect_b32 s83, 0x80, 0
	s_add_u32 s76, s76, s83
	s_addc_u32 s77, s77, 0
	s_add_u32 vcc_lo, vcc_lo, s83
	s_addc_u32 vcc_hi, vcc_hi, 0
	s_add_i32 s82, s82, 1
	s_setprio 0
	s_barrier
	v_add_u32_e32 v136, 0x1c000, v147
	ds_read_b128 v[166:169], v136
	ds_read_b128 v[170:173], v136 offset:1024
	ds_read_b128 v[174:177], v136 offset:2048
	ds_read_b128 v[178:181], v136 offset:3072
	ds_read_b128 v[202:205], v165 offset:49152
	ds_read_b128 v[208:211], v165 offset:50176
	ds_read_b128 v[212:215], v165 offset:51200
	ds_read_b128 v[216:219], v165 offset:52224
	ds_read_b128 v[220:223], v165 offset:53248
	ds_read_b128 v[224:227], v165 offset:54272
	ds_read_b128 v[228:231], v165 offset:55296
	ds_read_b128 v[232:235], v165 offset:56320
	v_lshl_add_u64 v[136:137], s[76:77], 0, v[0:1]
	s_add_i32 m0, s94, 0x4000
	v_lshl_add_u64 v[144:145], s[76:77], 0, v[130:131]
	global_load_lds_dwordx4 v[136:137], off
	s_add_i32 m0, s94, 0x6000
	s_nop 0
	global_load_lds_dwordx4 v[144:145], off
	s_waitcnt vmcnt(6)
	s_waitcnt lgkmcnt(0)
	s_barrier
	s_setprio 1
	v_mfma_f32_16x16x32_bf16 v[54:57], v[166:169], v[202:205], v[54:57]
	v_mfma_f32_16x16x32_bf16 v[50:53], v[174:177], v[202:205], v[50:53]
	v_mfma_f32_16x16x32_bf16 v[38:41], v[166:169], v[212:215], v[38:41]
	v_lshl_add_u64 v[182:183], vcc, 0, v[0:1]
	s_add_i32 m0, s93, 0x14000
	v_lshl_add_u64 v[236:237], vcc, 0, v[130:131]
	global_load_lds_dwordx4 v[182:183], off
	v_mfma_f32_16x16x32_bf16 v[34:37], v[174:177], v[212:215], v[34:37]
	v_mfma_f32_16x16x32_bf16 v[22:25], v[166:169], v[220:223], v[22:25]
	v_mfma_f32_16x16x32_bf16 v[18:21], v[174:177], v[220:223], v[18:21]
	v_mfma_f32_16x16x32_bf16 v[6:9], v[166:169], v[228:231], v[6:9]
	v_mfma_f32_16x16x32_bf16 v[2:5], v[174:177], v[228:231], v[2:5]
	v_mfma_f32_16x16x32_bf16 v[54:57], v[170:173], v[208:211], v[54:57]
	s_add_i32 m0, s93, 0x16000
	s_nop 0
	global_load_lds_dwordx4 v[236:237], off
	v_mfma_f32_16x16x32_bf16 v[50:53], v[178:181], v[208:211], v[50:53]
	v_mfma_f32_16x16x32_bf16 v[38:41], v[170:173], v[216:219], v[38:41]
	v_mfma_f32_16x16x32_bf16 v[34:37], v[178:181], v[216:219], v[34:37]
	v_mfma_f32_16x16x32_bf16 v[22:25], v[170:173], v[224:227], v[22:25]
	v_mfma_f32_16x16x32_bf16 v[18:21], v[178:181], v[224:227], v[18:21]
	v_mfma_f32_16x16x32_bf16 v[6:9], v[170:173], v[232:235], v[6:9]
	v_mfma_f32_16x16x32_bf16 v[2:5], v[178:181], v[232:235], v[2:5]
	s_cmp_lt_u32 s82, s59
	s_cselect_b32 s83, 0x80, 0
	s_add_u32 s76, s76, s83
	s_addc_u32 s77, s77, 0
	s_add_u32 vcc_lo, vcc_lo, s83
	s_addc_u32 vcc_hi, vcc_hi, 0
	s_add_i32 s82, s82, 1
	s_setprio 0
	s_barrier
; #define PG8_STAGE(bufoff, gbase, voff) do { _Pragma("unroll") for (int _i = 0; _i < 2; ++_i) \
;         __builtin_amdgcn_global_load_lds((const unsigned*)((const char*)(gbase) + (voff)[_i]), (PG8_LAS unsigned*)(lds + (bufoff) + ldsw + _i * 8192), 16, 0, 0); } while (0)
; #define PG8_LDA(dst, b, h) do { _Pragma("unroll") for (int m = 0; m < 4; ++m) _Pragma("unroll") for (int k = 0; k < 2; ++k) dst[m][k] = *(const PG8_LAS bf16x8*)(lds + PG8_SA(b, h) + aoff + m * 2048 + k * 1024); } while (0)
; #define PG8_LDB(dst, b, h) do { _Pragma("unroll") for (int n = 0; n < 2; ++n) _Pragma("unroll") for (int k = 0; k < 2; ++k) dst[n][k] = *(const PG8_LAS bf16x8*)(lds + PG8_SB(b, h) + boff + n * 2048 + k * 1024); } while (0)
; #define PG8_MMA(ai, bj, At, Bt) do { __builtin_amdgcn_s_setprio(1); _Pragma("unroll") for (int m = 0; m < 4; ++m) _Pragma("unroll") for (int n = 0; n < 2; ++n) _Pragma("unroll") for (int k = 0; k < 2; ++k) \
;         acc[ai][bj][m][n] = __builtin_amdgcn_mfma_f32_16x16x32_bf16(Bt[n][k], At[m][k], acc[ai][bj][m][n], 0, 0, 0); __builtin_amdgcn_s_setprio(0); } while (0)
; #define PG8_WAIT_V(n) asm volatile("s_waitcnt vmcnt(" #n ")" ::: "memory")
; template <class Epi, class Sched, bool ALIGN_EPI = false, bool SP2 = false>
; __device__ __forceinline__ void gemm_phase(PG8_LAS unsigned char* lds, const Gemm g, const Sched& S, const Epi& E) {
;     ...
;             PG8_LDB(B0, 0, 0); PG8_LDB(B1, 0, 1); PG8_SCHED; PG8_LDA(At, 0, 0); PG8_STAGE(PG8_SA(1, 1), a1 + hstep, voffA);
;             PG8_WAIT_V(8); PG8_WAIT_L(0); PG8_BAR; PG8_MMA(0, 0, At, B0); PG8_MMA(0, 1, At, B1); PG8_BAR; PG8_SCHED;
;             PG8_LDA(At, 0, 1); PG8_STAGE(PG8_SB(0, 0), b2, voffB); PG8_STAGE(PG8_SB(0, 1), b2 + hstep, voffB); PG8_STAGE(PG8_SA(0, 0), a2, voffA);
;             PG8_WAIT_V(8); PG8_WAIT_L(0); PG8_BAR; PG8_MMA(1, 0, At, B0); PG8_MMA(1, 1, At, B1); PG8_BAR; PG8_SCHED;
;             PG8_LDB(B0, 1, 0); PG8_LDB(B1, 1, 1); PG8_SCHED; PG8_LDA(At, 1, 0); PG8_STAGE(PG8_SA(0, 1), a2 + hstep, voffA);
;             PG8_WAIT_V(8); PG8_WAIT_L(0); PG8_BAR; PG8_MMA(0, 0, At, B0); PG8_MMA(0, 1, At, B1); PG8_BAR; PG8_SCHED;
;             PG8_LDA(At, 1, 1); PG8_STAGE(PG8_SB(1, 0), b3, voffB); PG8_STAGE(PG8_SB(1, 1), b3 + hstep, voffB); PG8_STAGE(PG8_SA(1, 0), a3, voffA);
;             PG8_WAIT_V(8); PG8_WAIT_L(0); PG8_BAR; PG8_MMA(1, 0, At, B0); PG8_MMA(1, 1, At, B1); PG8_BAR; PG8_SCHED;
	v_add_u32_e32 v136, 0x10000, v147
	ds_read_b128 v[166:169], v136
	ds_read_b128 v[170:173], v136 offset:1024
	ds_read_b128 v[174:177], v136 offset:2048
	ds_read_b128 v[178:181], v136 offset:3072
	ds_read_b128 v[202:205], v165
	ds_read_b128 v[208:211], v165 offset:1024
	ds_read_b128 v[212:215], v165 offset:2048
	ds_read_b128 v[216:219], v165 offset:3072
	ds_read_b128 v[220:223], v165 offset:4096
	ds_read_b128 v[224:227], v165 offset:5120
	ds_read_b128 v[228:231], v165 offset:6144
	ds_read_b128 v[232:235], v165 offset:7168
	v_lshl_add_u64 v[136:137], s[76:77], 0, v[0:1]
	s_add_i32 m0, s94, 0xc000
	v_lshl_add_u64 v[144:145], s[76:77], 0, v[130:131]
	global_load_lds_dwordx4 v[136:137], off
	s_add_i32 m0, s94, 0xe000
	s_nop 0
	global_load_lds_dwordx4 v[144:145], off
	s_waitcnt vmcnt(6)
	s_waitcnt lgkmcnt(0)
	s_barrier
	s_setprio 1
	v_mfma_f32_16x16x32_bf16 v[54:57], v[166:169], v[202:205], v[54:57]
	v_mfma_f32_16x16x32_bf16 v[50:53], v[174:177], v[202:205], v[50:53]
	v_mfma_f32_16x16x32_bf16 v[38:41], v[166:169], v[212:215], v[38:41]
	v_lshl_add_u64 v[182:183], vcc, 0, v[0:1]
	s_add_i32 m0, s93, 0x1c000
	v_lshl_add_u64 v[236:237], vcc, 0, v[130:131]
	global_load_lds_dwordx4 v[182:183], off
	v_mfma_f32_16x16x32_bf16 v[34:37], v[174:177], v[212:215], v[34:37]
	v_mfma_f32_16x16x32_bf16 v[22:25], v[166:169], v[220:223], v[22:25]
	v_mfma_f32_16x16x32_bf16 v[18:21], v[174:177], v[220:223], v[18:21]
	v_mfma_f32_16x16x32_bf16 v[6:9], v[166:169], v[228:231], v[6:9]
	v_mfma_f32_16x16x32_bf16 v[2:5], v[174:177], v[228:231], v[2:5]
	v_mfma_f32_16x16x32_bf16 v[54:57], v[170:173], v[208:211], v[54:57]
	s_add_i32 m0, s93, 0x1e000
	s_nop 0
	global_load_lds_dwordx4 v[236:237], off
	v_mfma_f32_16x16x32_bf16 v[50:53], v[178:181], v[208:211], v[50:53]
	v_mfma_f32_16x16x32_bf16 v[38:41], v[170:173], v[216:219], v[38:41]
	v_mfma_f32_16x16x32_bf16 v[34:37], v[178:181], v[216:219], v[34:37]
	v_mfma_f32_16x16x32_bf16 v[22:25], v[170:173], v[224:227], v[22:25]
	v_mfma_f32_16x16x32_bf16 v[18:21], v[178:181], v[224:227], v[18:21]
	v_mfma_f32_16x16x32_bf16 v[6:9], v[170:173], v[232:235], v[6:9]
	v_mfma_f32_16x16x32_bf16 v[2:5], v[178:181], v[232:235], v[2:5]
	s_cmp_lt_u32 s82, s59
	s_cselect_b32 s83, 0x80, 0
	s_add_u32 s76, s76, s83
	s_addc_u32 s77, s77, 0
	s_add_u32 vcc_lo, vcc_lo, s83
	s_addc_u32 vcc_hi, vcc_hi, 0
	s_add_i32 s82, s82, 1
	s_setprio 0
	s_barrier
	v_add_u32_e32 v136, 0x18000, v147
	ds_read_b128 v[166:169], v136
	ds_read_b128 v[170:173], v136 offset:1024
	ds_read_b128 v[174:177], v136 offset:2048
	ds_read_b128 v[178:181], v136 offset:3072
	ds_read_b128 v[202:205], v165 offset:32768
	ds_read_b128 v[208:211], v165 offset:33792
	ds_read_b128 v[212:215], v165 offset:34816
	ds_read_b128 v[216:219], v165 offset:35840
	ds_read_b128 v[220:223], v165 offset:36864
	ds_read_b128 v[224:227], v165 offset:37888
	ds_read_b128 v[228:231], v165 offset:38912
	ds_read_b128 v[232:235], v165 offset:39936
	v_lshl_add_u64 v[136:137], s[76:77], 0, v[0:1]
	s_add_i32 m0, s94, 0x0
	v_lshl_add_u64 v[144:145], s[76:77], 0, v[130:131]
	global_load_lds_dwordx4 v[136:137], off
	s_add_i32 m0, s94, 0x2000
	s_nop 0
	global_load_lds_dwordx4 v[144:145], off
	s_waitcnt vmcnt(6)
	s_waitcnt lgkmcnt(0)
	s_barrier
	s_setprio 1
	v_mfma_f32_16x16x32_bf16 v[54:57], v[166:169], v[202:205], v[54:57]
	v_mfma_f32_16x16x32_bf16 v[50:53], v[174:177], v[202:205], v[50:53]
	v_mfma_f32_16x16x32_bf16 v[38:41], v[166:169], v[212:215], v[38:41]
	v_lshl_add_u64 v[182:183], vcc, 0, v[0:1]
	s_add_i32 m0, s93, 0x10000
	v_lshl_add_u64 v[236:237], vcc, 0, v[130:131]
	global_load_lds_dwordx4 v[182:183], off
	v_mfma_f32_16x16x32_bf16 v[34:37], v[174:177], v[212:215], v[34:37]
	v_mfma_f32_16x16x32_bf16 v[22:25], v[166:169], v[220:223], v[22:25]
	v_mfma_f32_16x16x32_bf16 v[18:21], v[174:177], v[220:223], v[18:21]
	v_mfma_f32_16x16x32_bf16 v[6:9], v[166:169], v[228:231], v[6:9]
	v_mfma_f32_16x16x32_bf16 v[2:5], v[174:177], v[228:231], v[2:5]
	v_mfma_f32_16x16x32_bf16 v[54:57], v[170:173], v[208:211], v[54:57]
	s_add_i32 m0, s93, 0x12000
	s_nop 0
	global_load_lds_dwordx4 v[236:237], off
	v_mfma_f32_16x16x32_bf16 v[50:53], v[178:181], v[208:211], v[50:53]
	v_mfma_f32_16x16x32_bf16 v[38:41], v[170:173], v[216:219], v[38:41]
	v_mfma_f32_16x16x32_bf16 v[34:37], v[178:181], v[216:219], v[34:37]
	v_mfma_f32_16x16x32_bf16 v[22:25], v[170:173], v[224:227], v[22:25]
	v_mfma_f32_16x16x32_bf16 v[18:21], v[178:181], v[224:227], v[18:21]
	v_mfma_f32_16x16x32_bf16 v[6:9], v[170:173], v[232:235], v[6:9]
	v_mfma_f32_16x16x32_bf16 v[2:5], v[178:181], v[232:235], v[2:5]
	s_cmp_lt_u32 s82, s59
	s_cselect_b32 s83, 0x80, 0
	s_add_u32 s76, s76, s83
	s_addc_u32 s77, s77, 0
	s_add_u32 vcc_lo, vcc_lo, s83
	s_addc_u32 vcc_hi, vcc_hi, 0
	s_add_i32 s82, s82, 1
	s_setprio 0
	s_barrier
	s_add_i32 s83, s82, -3
	s_cmp_lt_u32 s83, s79
	s_cbranch_scc1 .Lkq_4_loop
